# v24 + rmsnorm row loops unrolled by two with two rows of x in flight per wave (register sets alternate)
# speedup vs baseline: 1.0575x; 1.0006x over previous
; __device__ __forceinline__ int opaque_tid() { int t = threadIdx.x; asm volatile("" : "+v"(t)); return t; }
; __device__ __forceinline__ void st_bf4(bf16_t* p, const f32x4 v) { u32x2 w; w.x = cvt_pk_bf16(v[0], v[1]); w.y = cvt_pk_bf16(v[2], v[3]); *(u32x2*)p = w; }
; template <bool F32OUT>
; __device__ __forceinline__ void rmsnorm_rows(const float* x, const float* w, bf16_t* outb, float* outf) {
;     const int tid_ = opaque_tid(); const int lane = tid_ & 63, gw = blockIdx.x * 8 + (tid_ >> 6), nw = gridDim.x * 8;
;     for (int row = gw; row < T_; row += nw) {
;         const float* xr = x + (size_t)row * D_; f32x4 v[8]; float ss = 0.f;
; #pragma unroll
;         for (int i = 0; i < 8; ++i) { v[i] = *(const f32x4*)(xr + i * 256 + lane * 4); ss += v[i][0] * v[i][0] + v[i][1] * v[i][1] + v[i][2] * v[i][2] + v[i][3] * v[i][3]; }
;         ss = wave_sum(ss);
;         const float rstd = 1.0f / sqrtf(ss * (1.0f / D_) + 1e-6f);
; #pragma unroll
;         for (int i = 0; i < 8; ++i) { const f32x4 wv = *(const f32x4*)(w + i * 256 + lane * 4); const f32x4 y = v[i] * rstd * wv;
;             if (F32OUT) *(f32x4*)(outf + (size_t)row * D_ + i * 256 + lane * 4) = y; else st_bf4(outb + (size_t)row * D_ + i * 256 + lane * 4, y); }
.LBB0_114:
	v_mov_b32_e32 v0, v192
	s_lshl_b32 s0, s2, 3
	v_ashrrev_i32_e32 v1, 6, v0
	v_writelane_b32 v248, s0, 22
	v_add_u32_e32 v16, s0, v1
	s_mov_b32 s0, 0x8000
	s_lshl_b32 s42, s68, 3
	v_cmp_gt_i32_e32 vcc, s0, v16
	v_mbcnt_lo_u32_b32 v193, -1, 0
	s_and_saveexec_b64 s[6:7], vcc
	s_cbranch_execz .LBB0_117
	v_mbcnt_hi_u32_b32 v1, -1, v193
	v_and_b32_e32 v2, 64, v1
	v_add_u32_e32 v2, 64, v2
	v_xor_b32_e32 v3, 32, v1
	v_cmp_lt_i32_e32 vcc, v3, v2
	v_ashrrev_i32_e32 v17, 31, v16
	v_and_b32_e32 v4, 63, v0
	v_cndmask_b32_e32 v3, v1, v3, vcc
	v_lshlrev_b32_e32 v32, 2, v3
	v_xor_b32_e32 v3, 16, v1
	v_cmp_lt_i32_e32 vcc, v3, v2
	s_mov_b64 s[0:1], 0x1000
	s_mov_b64 s[4:5], 0x1400
	v_cndmask_b32_e32 v3, v1, v3, vcc
	v_lshlrev_b32_e32 v33, 2, v3
	v_xor_b32_e32 v3, 8, v1
	v_cmp_lt_i32_e32 vcc, v3, v2
	s_ashr_i32 s43, s42, 31
	s_lshl_b64 s[8:9], s[42:43], 13
	v_cndmask_b32_e32 v3, v1, v3, vcc
	v_lshlrev_b32_e32 v34, 2, v3
	v_xor_b32_e32 v3, 4, v1
	v_cmp_lt_i32_e32 vcc, v3, v2
	s_lshl_b64 s[10:11], s[42:43], 12
	s_mov_b64 s[14:15], 0
	v_cndmask_b32_e32 v3, v1, v3, vcc
	v_lshlrev_b32_e32 v35, 2, v3
	v_xor_b32_e32 v3, 2, v1
	v_cmp_lt_i32_e32 vcc, v3, v2
	v_mov_b32_e32 v38, 0x260
	s_nop 0
	v_cndmask_b32_e32 v3, v1, v3, vcc
	v_lshlrev_b32_e32 v36, 2, v3
	v_xor_b32_e32 v3, 1, v1
	v_cmp_lt_i32_e32 vcc, v3, v2
	s_nop 1
	v_cndmask_b32_e32 v1, v1, v3, vcc
	v_lshlrev_b32_e32 v37, 2, v1
	v_lshlrev_b32_e32 v1, 4, v0
	v_and_b32_e32 v2, 0x3f0, v1
	v_mov_b32_e32 v3, 0
	v_lshl_add_u64 v[18:19], s[40:41], 0, v[2:3]
	v_lshlrev_b64 v[2:3], 13, v[16:17]
	v_lshl_or_b32 v2, v4, 4, v2
	v_lshl_add_u64 v[0:1], s[36:37], 0, v[2:3]
	v_lshl_add_u64 v[28:29], v[0:1], 0, s[0:1]
	v_lshlrev_b64 v[0:1], 12, v[16:17]
	v_lshl_add_u64 v[22:23], v[18:19], 0, s[4:5]
	s_mov_b64 s[4:5], 0x1800
	v_lshl_or_b32 v0, v4, 3, v0
	v_lshl_add_u64 v[20:21], v[18:19], 0, s[0:1]
	v_lshl_add_u64 v[24:25], v[18:19], 0, s[4:5]
	s_mov_b64 s[4:5], 0x1c00
	v_lshl_add_u64 v[0:1], s[30:31], 0, v[0:1]
	s_mov_b64 s[0:1], 0x15550800
	v_lshl_add_u64 v[26:27], v[18:19], 0, s[4:5]
	v_lshl_add_u64 v[30:31], v[0:1], 0, s[0:1]
	v_mov_b32_e32 v17, 0x358637bd
	s_mov_b32 s0, 0xf800000
	s_movk_i32 s1, 0x7fff
	global_load_dwordx4 v[100:103], v[18:19], off
	global_load_dwordx4 v[104:107], v[18:19], off offset:1024
	global_load_dwordx4 v[108:111], v[18:19], off offset:2048
	global_load_dwordx4 v[112:115], v[18:19], off offset:3072
	global_load_dwordx4 v[116:119], v[20:21], off
	global_load_dwordx4 v[120:123], v[22:23], off
	global_load_dwordx4 v[124:127], v[24:25], off
	global_load_dwordx4 v[128:131], v[26:27], off
	global_load_dwordx4 v[220:223], v[28:29], off offset:2048
	global_load_dwordx4 v[224:227], v[28:29], off offset:3072
	global_load_dwordx4 v[196:199], v[28:29], off offset:-4096
	global_load_dwordx4 v[200:203], v[28:29], off offset:-3072
	global_load_dwordx4 v[204:207], v[28:29], off offset:-2048
	global_load_dwordx4 v[208:211], v[28:29], off offset:-1024
	global_load_dwordx4 v[212:215], v[28:29], off
	global_load_dwordx4 v[216:219], v[28:29], off offset:1024
	v_add_u32_e32 v16, s42, v16
	v_lshl_add_u64 v[28:29], v[28:29], 0, s[8:9]
	v_cmp_lt_i32_e32 vcc, s1, v16
	s_mov_b64 s[88:89], vcc
	s_mov_b64 s[86:87], exec
	s_andn2_b64 exec, exec, s[88:89]
	global_load_dwordx4 v[188:191], v[28:29], off offset:2048
	global_load_dwordx4 v[228:231], v[28:29], off offset:3072
	global_load_dwordx4 v[164:167], v[28:29], off offset:-4096
	global_load_dwordx4 v[168:171], v[28:29], off offset:-3072
	global_load_dwordx4 v[172:175], v[28:29], off offset:-2048
	global_load_dwordx4 v[176:179], v[28:29], off offset:-1024
	global_load_dwordx4 v[180:183], v[28:29], off
	global_load_dwordx4 v[184:187], v[28:29], off offset:1024
	s_mov_b64 exec, s[86:87]
	v_add_u32_e32 v16, s42, v16
	v_lshl_add_u64 v[28:29], v[28:29], 0, s[8:9]
	s_waitcnt vmcnt(0)
.LBB0_116:
	s_waitcnt vmcnt(16)
	v_mov_b32_e32 v40, v196
	v_mov_b32_e32 v41, v197
	v_mov_b32_e32 v42, v198
	v_mov_b32_e32 v43, v199
	v_mov_b32_e32 v44, v200
	v_mov_b32_e32 v45, v201
	v_mov_b32_e32 v46, v202
	v_mov_b32_e32 v47, v203
	v_mov_b32_e32 v48, v204
	v_mov_b32_e32 v49, v205
	v_mov_b32_e32 v50, v206
	v_mov_b32_e32 v51, v207
	v_mov_b32_e32 v52, v208
	v_mov_b32_e32 v53, v209
	v_mov_b32_e32 v54, v210
	v_mov_b32_e32 v55, v211
	v_mov_b32_e32 v12, v212
	v_mov_b32_e32 v13, v213
	v_mov_b32_e32 v14, v214
	v_mov_b32_e32 v15, v215
	v_mov_b32_e32 v8, v216
	v_mov_b32_e32 v9, v217
	v_mov_b32_e32 v10, v218
	v_mov_b32_e32 v11, v219
	v_mov_b32_e32 v4, v220
	v_mov_b32_e32 v5, v221
	v_mov_b32_e32 v6, v222
	v_mov_b32_e32 v7, v223
	v_mov_b32_e32 v0, v224
	v_mov_b32_e32 v1, v225
	v_mov_b32_e32 v2, v226
	v_mov_b32_e32 v3, v227
	s_or_b64 s[14:15], s[88:89], s[14:15]
	v_cmp_lt_i32_e32 vcc, s1, v16
	s_or_b64 s[88:89], vcc, s[88:89]
	s_mov_b64 s[86:87], exec
	s_andn2_b64 exec, exec, s[88:89]
	global_load_dwordx4 v[220:223], v[28:29], off offset:2048
	global_load_dwordx4 v[224:227], v[28:29], off offset:3072
	global_load_dwordx4 v[196:199], v[28:29], off offset:-4096
	global_load_dwordx4 v[200:203], v[28:29], off offset:-3072
	global_load_dwordx4 v[204:207], v[28:29], off offset:-2048
	global_load_dwordx4 v[208:211], v[28:29], off offset:-1024
	global_load_dwordx4 v[212:215], v[28:29], off
	global_load_dwordx4 v[216:219], v[28:29], off offset:1024
	s_mov_b64 exec, s[86:87]
	v_add_u32_e32 v16, s42, v16
	v_lshl_add_u64 v[28:29], v[28:29], 0, s[8:9]
	v_mov_b32_e32 v62, v5
	v_mov_b32_e32 v63, v1
	v_mul_f32_e32 v39, v41, v41
	v_mul_f32_e32 v68, v45, v45
	v_mul_f32_e32 v69, v49, v49
	v_fmac_f32_e32 v39, v40, v40
	v_fmac_f32_e32 v68, v44, v44
	v_mul_f32_e32 v70, v53, v53
	v_fmac_f32_e32 v69, v48, v48
	v_fmac_f32_e32 v39, v42, v42
	v_fmac_f32_e32 v68, v46, v46
	v_mul_f32_e32 v71, v13, v13
	v_fmac_f32_e32 v70, v52, v52
	v_fmac_f32_e32 v69, v50, v50
	v_fmac_f32_e32 v39, v43, v43
	v_fmac_f32_e32 v68, v47, v47
	v_mul_f32_e32 v72, v9, v9
	v_fmac_f32_e32 v71, v12, v12
	v_fmac_f32_e32 v70, v54, v54
	v_fmac_f32_e32 v69, v51, v51
	v_add_f32_e32 v39, v39, v68
	v_mov_b32_e32 v60, v4
	v_mov_b32_e32 v61, v0
	v_pk_mul_f32 v[62:63], v[62:63], v[62:63]
	v_fmac_f32_e32 v72, v8, v8
	v_fmac_f32_e32 v71, v14, v14
	v_fmac_f32_e32 v70, v55, v55
	v_add_f32_e32 v39, v39, v69
	v_mov_b32_e32 v64, v6
	v_mov_b32_e32 v65, v2
	v_pk_fma_f32 v[60:61], v[60:61], v[60:61], v[62:63]
	v_fmac_f32_e32 v72, v10, v10
	v_fmac_f32_e32 v71, v15, v15
	v_add_f32_e32 v39, v39, v70
	v_mov_b32_e32 v66, v7
	v_mov_b32_e32 v67, v3
	v_pk_fma_f32 v[60:61], v[64:65], v[64:65], v[60:61]
	v_fmac_f32_e32 v72, v11, v11
	v_add_f32_e32 v39, v39, v71
	v_pk_fma_f32 v[60:61], v[66:67], v[66:67], v[60:61]
	v_add_f32_e32 v39, v39, v72
	v_add_f32_e32 v39, v39, v60
	v_add_f32_e32 v39, v39, v61
	ds_bpermute_b32 v60, v32, v39
	s_waitcnt lgkmcnt(0)
; __device__ __forceinline__ void st_bf4(bf16_t* p, const f32x4 v) { u32x2 w; w.x = cvt_pk_bf16(v[0], v[1]); w.y = cvt_pk_bf16(v[2], v[3]); *(u32x2*)p = w; }
; template <bool F32OUT>
; __device__ __forceinline__ void rmsnorm_rows(const float* x, const float* w, bf16_t* outb, float* outf) {
;     ...
;         ss = wave_sum(ss);
;         const float rstd = 1.0f / sqrtf(ss * (1.0f / D_) + 1e-6f);
; #pragma unroll
;         for (int i = 0; i < 8; ++i) { const f32x4 wv = *(const f32x4*)(w + i * 256 + lane * 4); const f32x4 y = v[i] * rstd * wv;
;             if (F32OUT) *(f32x4*)(outf + (size_t)row * D_ + i * 256 + lane * 4) = y; else st_bf4(outb + (size_t)row * D_ + i * 256 + lane * 4, y); }
	v_add_f32_e32 v39, v39, v60
	ds_bpermute_b32 v60, v33, v39
	s_waitcnt lgkmcnt(0)
	v_add_f32_e32 v39, v39, v60
	ds_bpermute_b32 v60, v34, v39
	s_waitcnt lgkmcnt(0)
	v_add_f32_e32 v39, v39, v60
	ds_bpermute_b32 v60, v35, v39
	s_waitcnt lgkmcnt(0)
	v_add_f32_e32 v39, v39, v60
	ds_bpermute_b32 v60, v36, v39
	s_waitcnt lgkmcnt(0)
	v_add_f32_e32 v39, v39, v60
	ds_bpermute_b32 v60, v37, v39
	s_waitcnt lgkmcnt(0)
	v_add_f32_e32 v39, v39, v60
	v_fmamk_f32 v39, v39, 0x3a000000, v17
	v_mul_f32_e32 v60, 0x4f800000, v39
	v_cmp_gt_f32_e32 vcc, s0, v39
	s_nop 1
	v_cndmask_b32_e32 v39, v39, v60, vcc
	v_sqrt_f32_e32 v60, v39
	s_nop 0
	v_add_u32_e32 v61, -1, v60
	v_add_u32_e32 v62, 1, v60
	v_fma_f32 v63, -v61, v60, v39
	v_fma_f32 v64, -v62, v60, v39
	v_cmp_ge_f32_e64 s[4:5], 0, v63
	s_nop 1
	v_cndmask_b32_e64 v60, v60, v61, s[4:5]
	v_cmp_lt_f32_e64 s[4:5], 0, v64
	s_nop 1
	v_cndmask_b32_e64 v60, v60, v62, s[4:5]
	v_mul_f32_e32 v61, 0x37800000, v60
	v_cndmask_b32_e32 v60, v60, v61, vcc
	v_cmp_class_f32_e32 vcc, v39, v38
	s_nop 1
	v_cndmask_b32_e32 v39, v60, v39, vcc
	v_div_scale_f32 v60, s[4:5], v39, v39, 1.0
	v_rcp_f32_e32 v62, v60
	v_div_scale_f32 v61, vcc, 1.0, v39, 1.0
	v_fma_f32 v63, -v60, v62, 1.0
	v_fmac_f32_e32 v62, v63, v62
	v_mul_f32_e32 v63, v61, v62
	v_fma_f32 v64, -v60, v63, v61
	v_fmac_f32_e32 v63, v64, v62
	v_fma_f32 v60, -v60, v63, v61
	v_div_fmas_f32 v60, v60, v62, v63
	v_div_fixup_f32 v60, v60, v39, 1.0
	v_pk_mul_f32 v[40:41], v[40:41], v[60:61] op_sel_hi:[1,0]
	v_pk_mul_f32 v[42:43], v[42:43], v[60:61] op_sel_hi:[1,0]
	v_pk_mul_f32 v[40:41], v[100:101], v[40:41]
	v_pk_mul_f32 v[42:43], v[102:103], v[42:43]
	v_cvt_pk_bf16_f32 v40, v40, v41
	s_nop 0
	v_cvt_pk_bf16_f32 v41, v42, v43
	global_store_dwordx2 v[30:31], v[40:41], off
	v_pk_mul_f32 v[44:45], v[44:45], v[60:61] op_sel_hi:[1,0]
	v_pk_mul_f32 v[46:47], v[46:47], v[60:61] op_sel_hi:[1,0]
	v_pk_mul_f32 v[44:45], v[104:105], v[44:45]
	v_pk_mul_f32 v[46:47], v[106:107], v[46:47]
	v_cvt_pk_bf16_f32 v44, v44, v45
	s_nop 0
	v_cvt_pk_bf16_f32 v45, v46, v47
	global_store_dwordx2 v[30:31], v[44:45], off offset:512
	v_pk_mul_f32 v[48:49], v[48:49], v[60:61] op_sel_hi:[1,0]
	v_pk_mul_f32 v[50:51], v[50:51], v[60:61] op_sel_hi:[1,0]
	v_pk_mul_f32 v[48:49], v[108:109], v[48:49]
	v_pk_mul_f32 v[50:51], v[110:111], v[50:51]
	v_cvt_pk_bf16_f32 v48, v48, v49
	s_nop 0
	v_cvt_pk_bf16_f32 v49, v50, v51
	global_store_dwordx2 v[30:31], v[48:49], off offset:1024
	v_pk_mul_f32 v[52:53], v[52:53], v[60:61] op_sel_hi:[1,0]
	v_pk_mul_f32 v[54:55], v[54:55], v[60:61] op_sel_hi:[1,0]
	v_pk_mul_f32 v[52:53], v[112:113], v[52:53]
	v_pk_mul_f32 v[54:55], v[114:115], v[54:55]
	v_cvt_pk_bf16_f32 v52, v52, v53
	s_nop 0
	v_cvt_pk_bf16_f32 v53, v54, v55
	global_store_dwordx2 v[30:31], v[52:53], off offset:1536
	v_pk_mul_f32 v[12:13], v[12:13], v[60:61] op_sel_hi:[1,0]
	v_pk_mul_f32 v[14:15], v[14:15], v[60:61] op_sel_hi:[1,0]
	v_pk_mul_f32 v[12:13], v[116:117], v[12:13]
	v_pk_mul_f32 v[14:15], v[118:119], v[14:15]
	v_cvt_pk_bf16_f32 v12, v12, v13
	s_nop 0
	v_cvt_pk_bf16_f32 v13, v14, v15
	global_store_dwordx2 v[30:31], v[12:13], off offset:2048
	v_pk_mul_f32 v[8:9], v[8:9], v[60:61] op_sel_hi:[1,0]
	v_pk_mul_f32 v[10:11], v[10:11], v[60:61] op_sel_hi:[1,0]
	v_pk_mul_f32 v[8:9], v[120:121], v[8:9]
	v_pk_mul_f32 v[10:11], v[122:123], v[10:11]
	v_cvt_pk_bf16_f32 v8, v8, v9
	s_nop 0
	v_cvt_pk_bf16_f32 v9, v10, v11
	global_store_dwordx2 v[30:31], v[8:9], off offset:2560
	v_pk_mul_f32 v[4:5], v[4:5], v[60:61] op_sel_hi:[1,0]
	v_pk_mul_f32 v[6:7], v[6:7], v[60:61] op_sel_hi:[1,0]
	v_pk_mul_f32 v[4:5], v[124:125], v[4:5]
	v_pk_mul_f32 v[6:7], v[126:127], v[6:7]
	v_cvt_pk_bf16_f32 v4, v4, v5
	s_nop 0
	v_cvt_pk_bf16_f32 v5, v6, v7
	global_store_dwordx2 v[30:31], v[4:5], off offset:3072
	v_pk_mul_f32 v[0:1], v[0:1], v[60:61] op_sel_hi:[1,0]
	v_pk_mul_f32 v[2:3], v[2:3], v[60:61] op_sel_hi:[1,0]
	v_pk_mul_f32 v[0:1], v[128:129], v[0:1]
	v_pk_mul_f32 v[2:3], v[130:131], v[2:3]
	v_cvt_pk_bf16_f32 v0, v0, v1
	s_nop 0
	v_cvt_pk_bf16_f32 v1, v2, v3
	global_store_dwordx2 v[30:31], v[0:1], off offset:3584
	v_lshl_add_u64 v[30:31], v[30:31], 0, s[10:11]
	s_andn2_b64 exec, exec, s[14:15]
	s_cbranch_execz .Lmy_rms3x_0
	s_waitcnt vmcnt(16)
	v_mov_b32_e32 v40, v164
	v_mov_b32_e32 v41, v165
	v_mov_b32_e32 v42, v166
	v_mov_b32_e32 v43, v167
	v_mov_b32_e32 v44, v168
	v_mov_b32_e32 v45, v169
	v_mov_b32_e32 v46, v170
	v_mov_b32_e32 v47, v171
	v_mov_b32_e32 v48, v172
	v_mov_b32_e32 v49, v173
	v_mov_b32_e32 v50, v174
	v_mov_b32_e32 v51, v175
	v_mov_b32_e32 v52, v176
	v_mov_b32_e32 v53, v177
	v_mov_b32_e32 v54, v178
	v_mov_b32_e32 v55, v179
	v_mov_b32_e32 v12, v180
	v_mov_b32_e32 v13, v181
	v_mov_b32_e32 v14, v182
	v_mov_b32_e32 v15, v183
	v_mov_b32_e32 v8, v184
	v_mov_b32_e32 v9, v185
	v_mov_b32_e32 v10, v186
	v_mov_b32_e32 v11, v187
	v_mov_b32_e32 v4, v188
	v_mov_b32_e32 v5, v189
	v_mov_b32_e32 v6, v190
	v_mov_b32_e32 v7, v191
	v_mov_b32_e32 v0, v228
	v_mov_b32_e32 v1, v229
	v_mov_b32_e32 v2, v230
	v_mov_b32_e32 v3, v231
	s_or_b64 s[14:15], s[88:89], s[14:15]
	v_cmp_lt_i32_e32 vcc, s1, v16
	s_or_b64 s[88:89], vcc, s[88:89]
	s_mov_b64 s[86:87], exec
	s_andn2_b64 exec, exec, s[88:89]
	global_load_dwordx4 v[188:191], v[28:29], off offset:2048
	global_load_dwordx4 v[228:231], v[28:29], off offset:3072
	global_load_dwordx4 v[164:167], v[28:29], off offset:-4096
	global_load_dwordx4 v[168:171], v[28:29], off offset:-3072
	global_load_dwordx4 v[172:175], v[28:29], off offset:-2048
	global_load_dwordx4 v[176:179], v[28:29], off offset:-1024
	global_load_dwordx4 v[180:183], v[28:29], off
	global_load_dwordx4 v[184:187], v[28:29], off offset:1024
; __device__ __forceinline__ void st_bf4(bf16_t* p, const f32x4 v) { u32x2 w; w.x = cvt_pk_bf16(v[0], v[1]); w.y = cvt_pk_bf16(v[2], v[3]); *(u32x2*)p = w; }
; template <bool F32OUT>
; __device__ __forceinline__ void rmsnorm_rows(const float* x, const float* w, bf16_t* outb, float* outf) {
;     ...
;         const float* xr = x + (size_t)row * D_; f32x4 v[8]; float ss = 0.f;
; #pragma unroll
;         for (int i = 0; i < 8; ++i) { v[i] = *(const f32x4*)(xr + i * 256 + lane * 4); ss += v[i][0] * v[i][0] + v[i][1] * v[i][1] + v[i][2] * v[i][2] + v[i][3] * v[i][3]; }
;         ss = wave_sum(ss);
;         const float rstd = 1.0f / sqrtf(ss * (1.0f / D_) + 1e-6f);
; #pragma unroll
;         for (int i = 0; i < 8; ++i) { const f32x4 wv = *(const f32x4*)(w + i * 256 + lane * 4); const f32x4 y = v[i] * rstd * wv;
;             if (F32OUT) *(f32x4*)(outf + (size_t)row * D_ + i * 256 + lane * 4) = y; else st_bf4(outb + (size_t)row * D_ + i * 256 + lane * 4, y); }
	s_mov_b64 exec, s[86:87]
	v_add_u32_e32 v16, s42, v16
	v_lshl_add_u64 v[28:29], v[28:29], 0, s[8:9]
	v_mov_b32_e32 v62, v5
	v_mov_b32_e32 v63, v1
	v_mul_f32_e32 v39, v41, v41
	v_mul_f32_e32 v68, v45, v45
	v_mul_f32_e32 v69, v49, v49
	v_fmac_f32_e32 v39, v40, v40
	v_fmac_f32_e32 v68, v44, v44
	v_mul_f32_e32 v70, v53, v53
	v_fmac_f32_e32 v69, v48, v48
	v_fmac_f32_e32 v39, v42, v42
	v_fmac_f32_e32 v68, v46, v46
	v_mul_f32_e32 v71, v13, v13
	v_fmac_f32_e32 v70, v52, v52
	v_fmac_f32_e32 v69, v50, v50
	v_fmac_f32_e32 v39, v43, v43
	v_fmac_f32_e32 v68, v47, v47
	v_mul_f32_e32 v72, v9, v9
	v_fmac_f32_e32 v71, v12, v12
	v_fmac_f32_e32 v70, v54, v54
	v_fmac_f32_e32 v69, v51, v51
	v_add_f32_e32 v39, v39, v68
	v_mov_b32_e32 v60, v4
	v_mov_b32_e32 v61, v0
	v_pk_mul_f32 v[62:63], v[62:63], v[62:63]
	v_fmac_f32_e32 v72, v8, v8
	v_fmac_f32_e32 v71, v14, v14
	v_fmac_f32_e32 v70, v55, v55
	v_add_f32_e32 v39, v39, v69
	v_mov_b32_e32 v64, v6
	v_mov_b32_e32 v65, v2
	v_pk_fma_f32 v[60:61], v[60:61], v[60:61], v[62:63]
	v_fmac_f32_e32 v72, v10, v10
	v_fmac_f32_e32 v71, v15, v15
	v_add_f32_e32 v39, v39, v70
	v_mov_b32_e32 v66, v7
	v_mov_b32_e32 v67, v3
	v_pk_fma_f32 v[60:61], v[64:65], v[64:65], v[60:61]
	v_fmac_f32_e32 v72, v11, v11
	v_add_f32_e32 v39, v39, v71
	v_pk_fma_f32 v[60:61], v[66:67], v[66:67], v[60:61]
	v_add_f32_e32 v39, v39, v72
	v_add_f32_e32 v39, v39, v60
	v_add_f32_e32 v39, v39, v61
	ds_bpermute_b32 v60, v32, v39
	s_waitcnt lgkmcnt(0)
	v_add_f32_e32 v39, v39, v60
	ds_bpermute_b32 v60, v33, v39
	s_waitcnt lgkmcnt(0)
	v_add_f32_e32 v39, v39, v60
	ds_bpermute_b32 v60, v34, v39
	s_waitcnt lgkmcnt(0)
	v_add_f32_e32 v39, v39, v60
	ds_bpermute_b32 v60, v35, v39
	s_waitcnt lgkmcnt(0)
	v_add_f32_e32 v39, v39, v60
	ds_bpermute_b32 v60, v36, v39
	s_waitcnt lgkmcnt(0)
	v_add_f32_e32 v39, v39, v60
	ds_bpermute_b32 v60, v37, v39
	s_waitcnt lgkmcnt(0)
	v_add_f32_e32 v39, v39, v60
	v_fmamk_f32 v39, v39, 0x3a000000, v17
	v_mul_f32_e32 v60, 0x4f800000, v39
	v_cmp_gt_f32_e32 vcc, s0, v39
	s_nop 1
	v_cndmask_b32_e32 v39, v39, v60, vcc
	v_sqrt_f32_e32 v60, v39
	s_nop 0
	v_add_u32_e32 v61, -1, v60
	v_add_u32_e32 v62, 1, v60
	v_fma_f32 v63, -v61, v60, v39
	v_fma_f32 v64, -v62, v60, v39
	v_cmp_ge_f32_e64 s[4:5], 0, v63
	s_nop 1
	v_cndmask_b32_e64 v60, v60, v61, s[4:5]
	v_cmp_lt_f32_e64 s[4:5], 0, v64
	s_nop 1
	v_cndmask_b32_e64 v60, v60, v62, s[4:5]
	v_mul_f32_e32 v61, 0x37800000, v60
	v_cndmask_b32_e32 v60, v60, v61, vcc
	v_cmp_class_f32_e32 vcc, v39, v38
	s_nop 1
	v_cndmask_b32_e32 v39, v60, v39, vcc
	v_div_scale_f32 v60, s[4:5], v39, v39, 1.0
	v_rcp_f32_e32 v62, v60
	v_div_scale_f32 v61, vcc, 1.0, v39, 1.0
	v_fma_f32 v63, -v60, v62, 1.0
	v_fmac_f32_e32 v62, v63, v62
	v_mul_f32_e32 v63, v61, v62
	v_fma_f32 v64, -v60, v63, v61
	v_fmac_f32_e32 v63, v64, v62
	v_fma_f32 v60, -v60, v63, v61
	v_div_fmas_f32 v60, v60, v62, v63
	v_div_fixup_f32 v60, v60, v39, 1.0
	v_pk_mul_f32 v[40:41], v[40:41], v[60:61] op_sel_hi:[1,0]
	v_pk_mul_f32 v[42:43], v[42:43], v[60:61] op_sel_hi:[1,0]
	v_pk_mul_f32 v[40:41], v[100:101], v[40:41]
	v_pk_mul_f32 v[42:43], v[102:103], v[42:43]
	v_cvt_pk_bf16_f32 v40, v40, v41
	s_nop 0
	v_cvt_pk_bf16_f32 v41, v42, v43
	global_store_dwordx2 v[30:31], v[40:41], off
	v_pk_mul_f32 v[44:45], v[44:45], v[60:61] op_sel_hi:[1,0]
	v_pk_mul_f32 v[46:47], v[46:47], v[60:61] op_sel_hi:[1,0]
	v_pk_mul_f32 v[44:45], v[104:105], v[44:45]
	v_pk_mul_f32 v[46:47], v[106:107], v[46:47]
	v_cvt_pk_bf16_f32 v44, v44, v45
	s_nop 0
	v_cvt_pk_bf16_f32 v45, v46, v47
	global_store_dwordx2 v[30:31], v[44:45], off offset:512
	v_pk_mul_f32 v[48:49], v[48:49], v[60:61] op_sel_hi:[1,0]
	v_pk_mul_f32 v[50:51], v[50:51], v[60:61] op_sel_hi:[1,0]
	v_pk_mul_f32 v[48:49], v[108:109], v[48:49]
	v_pk_mul_f32 v[50:51], v[110:111], v[50:51]
	v_cvt_pk_bf16_f32 v48, v48, v49
	s_nop 0
	v_cvt_pk_bf16_f32 v49, v50, v51
	global_store_dwordx2 v[30:31], v[48:49], off offset:1024
	v_pk_mul_f32 v[52:53], v[52:53], v[60:61] op_sel_hi:[1,0]
	v_pk_mul_f32 v[54:55], v[54:55], v[60:61] op_sel_hi:[1,0]
	v_pk_mul_f32 v[52:53], v[112:113], v[52:53]
	v_pk_mul_f32 v[54:55], v[114:115], v[54:55]
	v_cvt_pk_bf16_f32 v52, v52, v53
	s_nop 0
	v_cvt_pk_bf16_f32 v53, v54, v55
	global_store_dwordx2 v[30:31], v[52:53], off offset:1536
	v_pk_mul_f32 v[12:13], v[12:13], v[60:61] op_sel_hi:[1,0]
	v_pk_mul_f32 v[14:15], v[14:15], v[60:61] op_sel_hi:[1,0]
	v_pk_mul_f32 v[12:13], v[116:117], v[12:13]
	v_pk_mul_f32 v[14:15], v[118:119], v[14:15]
	v_cvt_pk_bf16_f32 v12, v12, v13
	s_nop 0
	v_cvt_pk_bf16_f32 v13, v14, v15
	global_store_dwordx2 v[30:31], v[12:13], off offset:2048
	v_pk_mul_f32 v[8:9], v[8:9], v[60:61] op_sel_hi:[1,0]
	v_pk_mul_f32 v[10:11], v[10:11], v[60:61] op_sel_hi:[1,0]
	v_pk_mul_f32 v[8:9], v[120:121], v[8:9]
	v_pk_mul_f32 v[10:11], v[122:123], v[10:11]
	v_cvt_pk_bf16_f32 v8, v8, v9
	s_nop 0
	v_cvt_pk_bf16_f32 v9, v10, v11
	global_store_dwordx2 v[30:31], v[8:9], off offset:2560
	v_pk_mul_f32 v[4:5], v[4:5], v[60:61] op_sel_hi:[1,0]
	v_pk_mul_f32 v[6:7], v[6:7], v[60:61] op_sel_hi:[1,0]
	v_pk_mul_f32 v[4:5], v[124:125], v[4:5]
	v_pk_mul_f32 v[6:7], v[126:127], v[6:7]
	v_cvt_pk_bf16_f32 v4, v4, v5
	s_nop 0
	v_cvt_pk_bf16_f32 v5, v6, v7
	global_store_dwordx2 v[30:31], v[4:5], off offset:3072
	v_pk_mul_f32 v[0:1], v[0:1], v[60:61] op_sel_hi:[1,0]
	v_pk_mul_f32 v[2:3], v[2:3], v[60:61] op_sel_hi:[1,0]
	v_pk_mul_f32 v[0:1], v[128:129], v[0:1]
	v_pk_mul_f32 v[2:3], v[130:131], v[2:3]
	v_cvt_pk_bf16_f32 v0, v0, v1
	s_nop 0
	v_cvt_pk_bf16_f32 v1, v2, v3
	global_store_dwordx2 v[30:31], v[0:1], off offset:3584
	v_lshl_add_u64 v[30:31], v[30:31], 0, s[10:11]
	s_andn2_b64 exec, exec, s[14:15]
	s_cbranch_execnz .LBB0_116
; __device__ __forceinline__ unsigned xb_ld(unsigned* p)              { return __hip_atomic_load(p, __ATOMIC_RELAXED, __HIP_MEMORY_SCOPE_AGENT); }
; __device__ __forceinline__ void xcd_barrier_complete(unsigned* bar, unsigned x, unsigned& nloc, unsigned& nx) {
;     const unsigned G = gridDim.x * gridDim.y * gridDim.z;
;     unsigned sum, cnt, mine, sp = 0u;
;     for (;;) {
;         sum = 0u; cnt = 0u; mine = 0u;
; #pragma unroll
;         for (unsigned j = 0; j < 16; ++j) { const unsigned c = xb_ld(&bar[XB_XCNT(j)]); sum += c; cnt += (c > 0u) ? 1u : 0u; mine = (j == x) ? c : mine; }
; __device__ __forceinline__ void xcd_barrier(const XcdBarrier& b) {
;     asm volatile("s_waitcnt vmcnt(0)" ::: "memory");
;     __syncthreads();
;     if (threadIdx.x == 0) {
;         unsigned* bar = b.bar;
;         __builtin_amdgcn_s_waitcnt(0);
;         unsigned nloc = b.st[0], nx = b.st[1];
;         if (nloc == 0u) { xcd_barrier_complete(bar, b.x, nloc, nx); b.st[0] = nloc; b.st[1] = nx; }
.Lmy_rms3x_0:
.LBB0_117:
	s_or_b64 exec, exec, s[6:7]
	s_waitcnt vmcnt(0)
	s_barrier
	s_mov_b64 s[4:5], exec
	v_readlane_b32 s0, v248, 20
	v_readlane_b32 s1, v248, 21
	s_and_b64 s[0:1], s[4:5], s[0:1]
	s_mov_b64 exec, s[0:1]
	s_cbranch_execz .LBB0_169
	s_add_i32 s0, 0, 0x22000
	v_mov_b32_e32 v0, s0
	s_waitcnt vmcnt(0) expcnt(0) lgkmcnt(0)
	ds_read_b32 v2, v0
	s_add_i32 s0, 0, 0x22004
	v_mov_b32_e32 v0, s0
	ds_read_b32 v0, v0
	s_waitcnt lgkmcnt(1)
	v_cmp_ne_u32_e32 vcc, 0, v2
	s_cbranch_vccnz .LBB0_133
	v_readlane_b32 s0, v248, 0
	v_readlane_b32 s1, v248, 1
	s_load_dword s1, s[0:1], 0x14
	s_mov_b32 s0, 1
	v_mov_b32_e32 v16, 0
	s_waitcnt lgkmcnt(0)
	s_lshr_b32 s3, s1, 16
	s_and_b32 s1, s1, 0xffff
	s_cmp_lg_u32 s1, 0
	s_cselect_b64 s[6:7], -1, 0
	s_cmp_lg_u64 s[6:7], 0
	s_addc_u32 s1, s69, 0
	s_cmp_lg_u32 s3, 0
	s_cselect_b64 s[6:7], -1, 0
	s_cmp_lg_u64 s[6:7], 0
	s_addc_u32 s3, s94, 0
	s_add_u32 s6, s30, 0x3e150a00
	s_addc_u32 s7, s31, 0
	s_add_u32 s8, s30, 0x3e150c00
	s_addc_u32 s9, s31, 0
	s_add_u32 s10, s30, 0x3e150d00
	s_addc_u32 s11, s31, 0
	s_add_u32 s14, s30, 0x3e150e00
	s_addc_u32 s15, s31, 0
	s_add_u32 s16, s30, 0x3e150f00
	s_addc_u32 s17, s31, 0
	s_add_u32 s18, s30, 0x3e151000
	s_addc_u32 s19, s31, 0
	s_add_u32 s20, s30, 0x3e151100
	s_addc_u32 s21, s31, 0
	s_add_u32 s22, s30, 0x3e151200
	s_addc_u32 s23, s31, 0
	s_add_u32 s24, s30, 0x3e151300
	s_addc_u32 s25, s31, 0
	s_add_u32 s38, s30, 0x3e151400
	s_addc_u32 s39, s31, 0
	s_add_u32 s44, s30, 0x3e151500
	s_addc_u32 s45, s31, 0
	s_add_u32 s48, s30, 0x3e151600
	s_addc_u32 s49, s31, 0
	s_add_u32 s52, s30, 0x3e151700
	s_addc_u32 s53, s31, 0
	s_add_u32 s54, s30, 0x3e151800
	s_addc_u32 s55, s31, 0
	s_add_u32 s56, s30, 0x3e151900
	s_addc_u32 s57, s31, 0
	s_add_u32 s58, s30, 0x3e151a00
	s_addc_u32 s59, s31, 0
	s_mul_i32 s1, s1, s68
	s_add_u32 s64, s30, 0x3e151b00
	s_mul_i32 s1, s1, s3
	s_addc_u32 s65, s31, 0
	s_branch .LBB0_121

; __device__ __forceinline__ int opaque_tid() { int t = threadIdx.x; asm volatile("" : "+v"(t)); return t; }
; __device__ __forceinline__ void st_bf4(bf16_t* p, const f32x4 v) { u32x2 w; w.x = cvt_pk_bf16(v[0], v[1]); w.y = cvt_pk_bf16(v[2], v[3]); *(u32x2*)p = w; }
; template <bool F32OUT>
; __device__ __forceinline__ void rmsnorm_rows(const float* x, const float* w, bf16_t* outb, float* outf) {
;     const int tid_ = opaque_tid(); const int lane = tid_ & 63, gw = blockIdx.x * 8 + (tid_ >> 6), nw = gridDim.x * 8;
;     for (int row = gw; row < T_; row += nw) {
;         const float* xr = x + (size_t)row * D_; f32x4 v[8]; float ss = 0.f;
; #pragma unroll
;         for (int i = 0; i < 8; ++i) { v[i] = *(const f32x4*)(xr + i * 256 + lane * 4); ss += v[i][0] * v[i][0] + v[i][1] * v[i][1] + v[i][2] * v[i][2] + v[i][3] * v[i][3]; }
;         ss = wave_sum(ss);
;         const float rstd = 1.0f / sqrtf(ss * (1.0f / D_) + 1e-6f);
; #pragma unroll
;         for (int i = 0; i < 8; ++i) { const f32x4 wv = *(const f32x4*)(w + i * 256 + lane * 4); const f32x4 y = v[i] * rstd * wv;
;             if (F32OUT) *(f32x4*)(outf + (size_t)row * D_ + i * 256 + lane * 4) = y; else st_bf4(outb + (size_t)row * D_ + i * 256 + lane * 4, y); }
.LBB0_313:
	s_or_b64 exec, exec, s[4:5]
	s_waitcnt lgkmcnt(0)
	v_mov_b32_e32 v0, v192
	s_barrier
	v_readlane_b32 s0, v248, 22
	v_ashrrev_i32_e32 v1, 6, v0
	s_nop 0
	v_add_u32_e32 v12, s0, v1
	s_mov_b32 s0, 0x8000
	v_cmp_gt_i32_e32 vcc, s0, v12
	s_and_saveexec_b64 s[6:7], vcc
	s_cbranch_execz .LBB0_316
	v_mbcnt_hi_u32_b32 v1, -1, v193
	v_and_b32_e32 v2, 64, v1
	v_add_u32_e32 v2, 64, v2
	v_xor_b32_e32 v3, 32, v1
	v_cmp_lt_i32_e32 vcc, v3, v2
	v_ashrrev_i32_e32 v13, 31, v12
	v_and_b32_e32 v4, 63, v0
	v_cndmask_b32_e32 v3, v1, v3, vcc
	v_lshlrev_b32_e32 v28, 2, v3
	v_xor_b32_e32 v3, 16, v1
	v_cmp_lt_i32_e32 vcc, v3, v2
	s_mov_b64 s[0:1], 0x1000
	s_mov_b64 s[4:5], 0x1400
	v_cndmask_b32_e32 v3, v1, v3, vcc
	v_lshlrev_b32_e32 v29, 2, v3
	v_xor_b32_e32 v3, 8, v1
	v_cmp_lt_i32_e32 vcc, v3, v2
	s_ashr_i32 s43, s42, 31
	s_lshl_b64 s[8:9], s[42:43], 13
	v_cndmask_b32_e32 v3, v1, v3, vcc
	v_lshlrev_b32_e32 v30, 2, v3
	v_xor_b32_e32 v3, 4, v1
	v_cmp_lt_i32_e32 vcc, v3, v2
	s_lshl_b64 s[10:11], s[42:43], 12
	s_mov_b64 s[14:15], 0
	v_cndmask_b32_e32 v3, v1, v3, vcc
	v_lshlrev_b32_e32 v31, 2, v3
	v_xor_b32_e32 v3, 2, v1
	v_cmp_lt_i32_e32 vcc, v3, v2
	v_mov_b32_e32 v34, 0x260
	s_nop 0
	v_cndmask_b32_e32 v3, v1, v3, vcc
	v_lshlrev_b32_e32 v32, 2, v3
	v_xor_b32_e32 v3, 1, v1
	v_cmp_lt_i32_e32 vcc, v3, v2
	s_nop 1
	v_cndmask_b32_e32 v1, v1, v3, vcc
	v_lshlrev_b32_e32 v33, 2, v1
	v_lshlrev_b32_e32 v1, 4, v0
	v_and_b32_e32 v2, 0x3f0, v1
	v_mov_b32_e32 v3, 0
	v_lshl_add_u64 v[14:15], s[46:47], 0, v[2:3]
	v_lshlrev_b64 v[2:3], 13, v[12:13]
	v_lshl_or_b32 v2, v4, 4, v2
	v_lshl_add_u64 v[0:1], s[28:29], 0, v[2:3]
	v_lshl_add_u64 v[24:25], v[0:1], 0, s[0:1]
	v_lshlrev_b64 v[0:1], 12, v[12:13]
	v_lshl_add_u64 v[18:19], v[14:15], 0, s[4:5]
	s_mov_b64 s[4:5], 0x1800
	v_lshl_or_b32 v0, v4, 3, v0
	v_lshl_add_u64 v[16:17], v[14:15], 0, s[0:1]
	v_lshl_add_u64 v[20:21], v[14:15], 0, s[4:5]
	s_mov_b64 s[4:5], 0x1c00
	v_lshl_add_u64 v[0:1], s[30:31], 0, v[0:1]
	s_mov_b64 s[0:1], 0x15550800
	v_lshl_add_u64 v[22:23], v[14:15], 0, s[4:5]
	v_lshl_add_u64 v[26:27], v[0:1], 0, s[0:1]
	v_mov_b32_e32 v13, 0x358637bd
	s_mov_b32 s0, 0xf800000
	s_movk_i32 s1, 0x7fff
	global_load_dwordx4 v[100:103], v[14:15], off
	global_load_dwordx4 v[104:107], v[14:15], off offset:1024
	global_load_dwordx4 v[108:111], v[14:15], off offset:2048
	global_load_dwordx4 v[112:115], v[14:15], off offset:3072
	global_load_dwordx4 v[116:119], v[16:17], off
	global_load_dwordx4 v[120:123], v[18:19], off
	global_load_dwordx4 v[124:127], v[20:21], off
	global_load_dwordx4 v[128:131], v[22:23], off
	global_load_dwordx4 v[196:199], v[24:25], off offset:-4096
	global_load_dwordx4 v[200:203], v[24:25], off offset:-3072
	global_load_dwordx4 v[204:207], v[24:25], off offset:-2048
	global_load_dwordx4 v[208:211], v[24:25], off offset:-1024
	global_load_dwordx4 v[212:215], v[24:25], off
	global_load_dwordx4 v[216:219], v[24:25], off offset:1024
	global_load_dwordx4 v[220:223], v[24:25], off offset:2048
	global_load_dwordx4 v[224:227], v[24:25], off offset:3072
	v_add_u32_e32 v12, s42, v12
	v_lshl_add_u64 v[24:25], v[24:25], 0, s[8:9]
	v_cmp_lt_i32_e32 vcc, s1, v12
	s_mov_b64 s[88:89], vcc
	s_mov_b64 s[86:87], exec
	s_andn2_b64 exec, exec, s[88:89]
	global_load_dwordx4 v[164:167], v[24:25], off offset:-4096
	global_load_dwordx4 v[168:171], v[24:25], off offset:-3072
	global_load_dwordx4 v[172:175], v[24:25], off offset:-2048
	global_load_dwordx4 v[176:179], v[24:25], off offset:-1024
	global_load_dwordx4 v[180:183], v[24:25], off
	global_load_dwordx4 v[184:187], v[24:25], off offset:1024
	global_load_dwordx4 v[188:191], v[24:25], off offset:2048
	global_load_dwordx4 v[228:231], v[24:25], off offset:3072
	s_mov_b64 exec, s[86:87]
	v_add_u32_e32 v12, s42, v12
	v_lshl_add_u64 v[24:25], v[24:25], 0, s[8:9]
	s_waitcnt vmcnt(0)
.LBB0_315:
	s_waitcnt vmcnt(16)
	v_mov_b32_e32 v36, v196
	v_mov_b32_e32 v37, v197
	v_mov_b32_e32 v38, v198
	v_mov_b32_e32 v39, v199
	v_mov_b32_e32 v40, v200
	v_mov_b32_e32 v41, v201
	v_mov_b32_e32 v42, v202
	v_mov_b32_e32 v43, v203
	v_mov_b32_e32 v44, v204
	v_mov_b32_e32 v45, v205
	v_mov_b32_e32 v46, v206
	v_mov_b32_e32 v47, v207
	v_mov_b32_e32 v48, v208
	v_mov_b32_e32 v49, v209
	v_mov_b32_e32 v50, v210
	v_mov_b32_e32 v51, v211
	v_mov_b32_e32 v52, v212
	v_mov_b32_e32 v53, v213
	v_mov_b32_e32 v54, v214
	v_mov_b32_e32 v55, v215
	v_mov_b32_e32 v8, v216
	v_mov_b32_e32 v9, v217
	v_mov_b32_e32 v10, v218
	v_mov_b32_e32 v11, v219
	v_mov_b32_e32 v4, v220
	v_mov_b32_e32 v5, v221
	v_mov_b32_e32 v6, v222
	v_mov_b32_e32 v7, v223
	v_mov_b32_e32 v0, v224
	v_mov_b32_e32 v1, v225
	v_mov_b32_e32 v2, v226
	v_mov_b32_e32 v3, v227
	s_or_b64 s[14:15], s[88:89], s[14:15]
	v_cmp_lt_i32_e32 vcc, s1, v12
	s_or_b64 s[88:89], vcc, s[88:89]
	s_mov_b64 s[86:87], exec
	s_andn2_b64 exec, exec, s[88:89]
	global_load_dwordx4 v[196:199], v[24:25], off offset:-4096
	global_load_dwordx4 v[200:203], v[24:25], off offset:-3072
	global_load_dwordx4 v[204:207], v[24:25], off offset:-2048
	global_load_dwordx4 v[208:211], v[24:25], off offset:-1024
	global_load_dwordx4 v[212:215], v[24:25], off
	global_load_dwordx4 v[216:219], v[24:25], off offset:1024
	global_load_dwordx4 v[220:223], v[24:25], off offset:2048
	global_load_dwordx4 v[224:227], v[24:25], off offset:3072
	s_mov_b64 exec, s[86:87]
	v_add_u32_e32 v12, s42, v12
	v_lshl_add_u64 v[24:25], v[24:25], 0, s[8:9]
	v_mul_f32_e32 v35, v37, v37
	v_mul_f32_e32 v68, v41, v41
	v_mul_f32_e32 v69, v45, v45
	v_fmac_f32_e32 v35, v36, v36
	v_fmac_f32_e32 v68, v40, v40
	v_mul_f32_e32 v70, v49, v49
	v_fmac_f32_e32 v69, v44, v44
	v_fmac_f32_e32 v35, v38, v38
	v_fmac_f32_e32 v68, v42, v42
	v_mul_f32_e32 v71, v53, v53
	v_fmac_f32_e32 v70, v48, v48
	v_fmac_f32_e32 v69, v46, v46
	v_fmac_f32_e32 v35, v39, v39
	v_fmac_f32_e32 v68, v43, v43
	v_mul_f32_e32 v72, v9, v9
	v_mov_b32_e32 v62, v5
	v_mov_b32_e32 v63, v1
	v_fmac_f32_e32 v71, v52, v52
	v_fmac_f32_e32 v70, v50, v50
	v_fmac_f32_e32 v69, v47, v47
	v_add_f32_e32 v35, v35, v68
	v_mov_b32_e32 v60, v4
	v_mov_b32_e32 v61, v0
	v_fmac_f32_e32 v72, v8, v8
	v_pk_mul_f32 v[62:63], v[62:63], v[62:63]
	v_fmac_f32_e32 v71, v54, v54
	v_fmac_f32_e32 v70, v51, v51
	v_add_f32_e32 v35, v35, v69
	v_mov_b32_e32 v64, v6
	v_mov_b32_e32 v65, v2
	v_fmac_f32_e32 v72, v10, v10
	v_pk_fma_f32 v[60:61], v[60:61], v[60:61], v[62:63]
	v_fmac_f32_e32 v71, v55, v55
	v_add_f32_e32 v35, v35, v70
	v_mov_b32_e32 v66, v7
	v_mov_b32_e32 v67, v3
	v_fmac_f32_e32 v72, v11, v11
	v_pk_fma_f32 v[60:61], v[64:65], v[64:65], v[60:61]
	v_add_f32_e32 v35, v35, v71
	v_pk_fma_f32 v[60:61], v[66:67], v[66:67], v[60:61]
	v_add_f32_e32 v35, v35, v72
	v_add_f32_e32 v35, v35, v60
	v_add_f32_e32 v35, v35, v61
	ds_bpermute_b32 v60, v28, v35
	s_waitcnt lgkmcnt(0)
; __device__ __forceinline__ void st_bf4(bf16_t* p, const f32x4 v) { u32x2 w; w.x = cvt_pk_bf16(v[0], v[1]); w.y = cvt_pk_bf16(v[2], v[3]); *(u32x2*)p = w; }
; template <bool F32OUT>
; __device__ __forceinline__ void rmsnorm_rows(const float* x, const float* w, bf16_t* outb, float* outf) {
;     ...
;         ss = wave_sum(ss);
;         const float rstd = 1.0f / sqrtf(ss * (1.0f / D_) + 1e-6f);
; #pragma unroll
;         for (int i = 0; i < 8; ++i) { const f32x4 wv = *(const f32x4*)(w + i * 256 + lane * 4); const f32x4 y = v[i] * rstd * wv;
;             if (F32OUT) *(f32x4*)(outf + (size_t)row * D_ + i * 256 + lane * 4) = y; else st_bf4(outb + (size_t)row * D_ + i * 256 + lane * 4, y); }
	v_add_f32_e32 v35, v35, v60
	ds_bpermute_b32 v60, v29, v35
	s_waitcnt lgkmcnt(0)
	v_add_f32_e32 v35, v35, v60
	ds_bpermute_b32 v60, v30, v35
	s_waitcnt lgkmcnt(0)
	v_add_f32_e32 v35, v35, v60
	ds_bpermute_b32 v60, v31, v35
	s_waitcnt lgkmcnt(0)
	v_add_f32_e32 v35, v35, v60
	ds_bpermute_b32 v60, v32, v35
	s_waitcnt lgkmcnt(0)
	v_add_f32_e32 v35, v35, v60
	ds_bpermute_b32 v60, v33, v35
	s_waitcnt lgkmcnt(0)
	v_add_f32_e32 v35, v35, v60
	v_fmamk_f32 v35, v35, 0x3a000000, v13
	v_mul_f32_e32 v60, 0x4f800000, v35
	v_cmp_gt_f32_e32 vcc, s0, v35
	s_nop 1
	v_cndmask_b32_e32 v35, v35, v60, vcc
	v_sqrt_f32_e32 v60, v35
	s_nop 0
	v_add_u32_e32 v61, -1, v60
	v_add_u32_e32 v62, 1, v60
	v_fma_f32 v63, -v61, v60, v35
	v_fma_f32 v64, -v62, v60, v35
	v_cmp_ge_f32_e64 s[4:5], 0, v63
	s_nop 1
	v_cndmask_b32_e64 v60, v60, v61, s[4:5]
	v_cmp_lt_f32_e64 s[4:5], 0, v64
	s_nop 1
	v_cndmask_b32_e64 v60, v60, v62, s[4:5]
	v_mul_f32_e32 v61, 0x37800000, v60
	v_cndmask_b32_e32 v60, v60, v61, vcc
	v_cmp_class_f32_e32 vcc, v35, v34
	s_nop 1
	v_cndmask_b32_e32 v35, v60, v35, vcc
	v_div_scale_f32 v60, s[4:5], v35, v35, 1.0
	v_rcp_f32_e32 v62, v60
	v_div_scale_f32 v61, vcc, 1.0, v35, 1.0
	v_fma_f32 v63, -v60, v62, 1.0
	v_fmac_f32_e32 v62, v63, v62
	v_mul_f32_e32 v63, v61, v62
	v_fma_f32 v64, -v60, v63, v61
	v_fmac_f32_e32 v63, v64, v62
	v_fma_f32 v60, -v60, v63, v61
	v_div_fmas_f32 v60, v60, v62, v63
	v_div_fixup_f32 v60, v60, v35, 1.0
	v_pk_mul_f32 v[36:37], v[36:37], v[60:61] op_sel_hi:[1,0]
	v_pk_mul_f32 v[38:39], v[38:39], v[60:61] op_sel_hi:[1,0]
	v_pk_mul_f32 v[36:37], v[100:101], v[36:37]
	v_pk_mul_f32 v[38:39], v[102:103], v[38:39]
	v_cvt_pk_bf16_f32 v36, v36, v37
	s_nop 0
	v_cvt_pk_bf16_f32 v37, v38, v39
	global_store_dwordx2 v[26:27], v[36:37], off
	v_pk_mul_f32 v[40:41], v[40:41], v[60:61] op_sel_hi:[1,0]
	v_pk_mul_f32 v[42:43], v[42:43], v[60:61] op_sel_hi:[1,0]
	v_pk_mul_f32 v[40:41], v[104:105], v[40:41]
	v_pk_mul_f32 v[42:43], v[106:107], v[42:43]
	v_cvt_pk_bf16_f32 v40, v40, v41
	s_nop 0
	v_cvt_pk_bf16_f32 v41, v42, v43
	global_store_dwordx2 v[26:27], v[40:41], off offset:512
	v_pk_mul_f32 v[44:45], v[44:45], v[60:61] op_sel_hi:[1,0]
	v_pk_mul_f32 v[46:47], v[46:47], v[60:61] op_sel_hi:[1,0]
	v_pk_mul_f32 v[44:45], v[108:109], v[44:45]
	v_pk_mul_f32 v[46:47], v[110:111], v[46:47]
	v_cvt_pk_bf16_f32 v44, v44, v45
	s_nop 0
	v_cvt_pk_bf16_f32 v45, v46, v47
	global_store_dwordx2 v[26:27], v[44:45], off offset:1024
	v_pk_mul_f32 v[48:49], v[48:49], v[60:61] op_sel_hi:[1,0]
	v_pk_mul_f32 v[50:51], v[50:51], v[60:61] op_sel_hi:[1,0]
	v_pk_mul_f32 v[48:49], v[112:113], v[48:49]
	v_pk_mul_f32 v[50:51], v[114:115], v[50:51]
	v_cvt_pk_bf16_f32 v48, v48, v49
	s_nop 0
	v_cvt_pk_bf16_f32 v49, v50, v51
	global_store_dwordx2 v[26:27], v[48:49], off offset:1536
	v_pk_mul_f32 v[52:53], v[52:53], v[60:61] op_sel_hi:[1,0]
	v_pk_mul_f32 v[54:55], v[54:55], v[60:61] op_sel_hi:[1,0]
	v_pk_mul_f32 v[52:53], v[116:117], v[52:53]
	v_pk_mul_f32 v[54:55], v[118:119], v[54:55]
	v_cvt_pk_bf16_f32 v52, v52, v53
	s_nop 0
	v_cvt_pk_bf16_f32 v53, v54, v55
	global_store_dwordx2 v[26:27], v[52:53], off offset:2048
	v_pk_mul_f32 v[8:9], v[8:9], v[60:61] op_sel_hi:[1,0]
	v_pk_mul_f32 v[10:11], v[10:11], v[60:61] op_sel_hi:[1,0]
	v_pk_mul_f32 v[8:9], v[120:121], v[8:9]
	v_pk_mul_f32 v[10:11], v[122:123], v[10:11]
	v_cvt_pk_bf16_f32 v8, v8, v9
	s_nop 0
	v_cvt_pk_bf16_f32 v9, v10, v11
	global_store_dwordx2 v[26:27], v[8:9], off offset:2560
	v_pk_mul_f32 v[4:5], v[4:5], v[60:61] op_sel_hi:[1,0]
	v_pk_mul_f32 v[6:7], v[6:7], v[60:61] op_sel_hi:[1,0]
	v_pk_mul_f32 v[4:5], v[124:125], v[4:5]
	v_pk_mul_f32 v[6:7], v[126:127], v[6:7]
	v_cvt_pk_bf16_f32 v4, v4, v5
	s_nop 0
	v_cvt_pk_bf16_f32 v5, v6, v7
	global_store_dwordx2 v[26:27], v[4:5], off offset:3072
	v_pk_mul_f32 v[0:1], v[0:1], v[60:61] op_sel_hi:[1,0]
	v_pk_mul_f32 v[2:3], v[2:3], v[60:61] op_sel_hi:[1,0]
	v_pk_mul_f32 v[0:1], v[128:129], v[0:1]
	v_pk_mul_f32 v[2:3], v[130:131], v[2:3]
	v_cvt_pk_bf16_f32 v0, v0, v1
	s_nop 0
	v_cvt_pk_bf16_f32 v1, v2, v3
	global_store_dwordx2 v[26:27], v[0:1], off offset:3584
	v_lshl_add_u64 v[26:27], v[26:27], 0, s[10:11]
	s_andn2_b64 exec, exec, s[14:15]
	s_cbranch_execz .Lmy_rms3x_1
	s_waitcnt vmcnt(16)
	v_mov_b32_e32 v36, v164
	v_mov_b32_e32 v37, v165
	v_mov_b32_e32 v38, v166
	v_mov_b32_e32 v39, v167
	v_mov_b32_e32 v40, v168
	v_mov_b32_e32 v41, v169
	v_mov_b32_e32 v42, v170
	v_mov_b32_e32 v43, v171
	v_mov_b32_e32 v44, v172
	v_mov_b32_e32 v45, v173
	v_mov_b32_e32 v46, v174
	v_mov_b32_e32 v47, v175
	v_mov_b32_e32 v48, v176
	v_mov_b32_e32 v49, v177
	v_mov_b32_e32 v50, v178
	v_mov_b32_e32 v51, v179
	v_mov_b32_e32 v52, v180
	v_mov_b32_e32 v53, v181
	v_mov_b32_e32 v54, v182
	v_mov_b32_e32 v55, v183
	v_mov_b32_e32 v8, v184
	v_mov_b32_e32 v9, v185
	v_mov_b32_e32 v10, v186
	v_mov_b32_e32 v11, v187
	v_mov_b32_e32 v4, v188
	v_mov_b32_e32 v5, v189
	v_mov_b32_e32 v6, v190
	v_mov_b32_e32 v7, v191
	v_mov_b32_e32 v0, v228
	v_mov_b32_e32 v1, v229
	v_mov_b32_e32 v2, v230
	v_mov_b32_e32 v3, v231
	s_or_b64 s[14:15], s[88:89], s[14:15]
	v_cmp_lt_i32_e32 vcc, s1, v12
	s_or_b64 s[88:89], vcc, s[88:89]
	s_mov_b64 s[86:87], exec
	s_andn2_b64 exec, exec, s[88:89]
	global_load_dwordx4 v[164:167], v[24:25], off offset:-4096
	global_load_dwordx4 v[168:171], v[24:25], off offset:-3072
	global_load_dwordx4 v[172:175], v[24:25], off offset:-2048
	global_load_dwordx4 v[176:179], v[24:25], off offset:-1024
	global_load_dwordx4 v[180:183], v[24:25], off
	global_load_dwordx4 v[184:187], v[24:25], off offset:1024
	global_load_dwordx4 v[188:191], v[24:25], off offset:2048
	global_load_dwordx4 v[228:231], v[24:25], off offset:3072
; __device__ __forceinline__ void st_bf4(bf16_t* p, const f32x4 v) { u32x2 w; w.x = cvt_pk_bf16(v[0], v[1]); w.y = cvt_pk_bf16(v[2], v[3]); *(u32x2*)p = w; }
; template <bool F32OUT>
; __device__ __forceinline__ void rmsnorm_rows(const float* x, const float* w, bf16_t* outb, float* outf) {
;     ...
;         const float* xr = x + (size_t)row * D_; f32x4 v[8]; float ss = 0.f;
; #pragma unroll
;         for (int i = 0; i < 8; ++i) { v[i] = *(const f32x4*)(xr + i * 256 + lane * 4); ss += v[i][0] * v[i][0] + v[i][1] * v[i][1] + v[i][2] * v[i][2] + v[i][3] * v[i][3]; }
;         ss = wave_sum(ss);
;         const float rstd = 1.0f / sqrtf(ss * (1.0f / D_) + 1e-6f);
; #pragma unroll
;         for (int i = 0; i < 8; ++i) { const f32x4 wv = *(const f32x4*)(w + i * 256 + lane * 4); const f32x4 y = v[i] * rstd * wv;
;             if (F32OUT) *(f32x4*)(outf + (size_t)row * D_ + i * 256 + lane * 4) = y; else st_bf4(outb + (size_t)row * D_ + i * 256 + lane * 4, y); }
	s_mov_b64 exec, s[86:87]
	v_add_u32_e32 v12, s42, v12
	v_lshl_add_u64 v[24:25], v[24:25], 0, s[8:9]
	v_mul_f32_e32 v35, v37, v37
	v_mul_f32_e32 v68, v41, v41
	v_mul_f32_e32 v69, v45, v45
	v_fmac_f32_e32 v35, v36, v36
	v_fmac_f32_e32 v68, v40, v40
	v_mul_f32_e32 v70, v49, v49
	v_fmac_f32_e32 v69, v44, v44
	v_fmac_f32_e32 v35, v38, v38
	v_fmac_f32_e32 v68, v42, v42
	v_mul_f32_e32 v71, v53, v53
	v_fmac_f32_e32 v70, v48, v48
	v_fmac_f32_e32 v69, v46, v46
	v_fmac_f32_e32 v35, v39, v39
	v_fmac_f32_e32 v68, v43, v43
	v_mul_f32_e32 v72, v9, v9
	v_mov_b32_e32 v62, v5
	v_mov_b32_e32 v63, v1
	v_fmac_f32_e32 v71, v52, v52
	v_fmac_f32_e32 v70, v50, v50
	v_fmac_f32_e32 v69, v47, v47
	v_add_f32_e32 v35, v35, v68
	v_mov_b32_e32 v60, v4
	v_mov_b32_e32 v61, v0
	v_fmac_f32_e32 v72, v8, v8
	v_pk_mul_f32 v[62:63], v[62:63], v[62:63]
	v_fmac_f32_e32 v71, v54, v54
	v_fmac_f32_e32 v70, v51, v51
	v_add_f32_e32 v35, v35, v69
	v_mov_b32_e32 v64, v6
	v_mov_b32_e32 v65, v2
	v_fmac_f32_e32 v72, v10, v10
	v_pk_fma_f32 v[60:61], v[60:61], v[60:61], v[62:63]
	v_fmac_f32_e32 v71, v55, v55
	v_add_f32_e32 v35, v35, v70
	v_mov_b32_e32 v66, v7
	v_mov_b32_e32 v67, v3
	v_fmac_f32_e32 v72, v11, v11
	v_pk_fma_f32 v[60:61], v[64:65], v[64:65], v[60:61]
	v_add_f32_e32 v35, v35, v71
	v_pk_fma_f32 v[60:61], v[66:67], v[66:67], v[60:61]
	v_add_f32_e32 v35, v35, v72
	v_add_f32_e32 v35, v35, v60
	v_add_f32_e32 v35, v35, v61
	ds_bpermute_b32 v60, v28, v35
	s_waitcnt lgkmcnt(0)
	v_add_f32_e32 v35, v35, v60
	ds_bpermute_b32 v60, v29, v35
	s_waitcnt lgkmcnt(0)
	v_add_f32_e32 v35, v35, v60
	ds_bpermute_b32 v60, v30, v35
	s_waitcnt lgkmcnt(0)
	v_add_f32_e32 v35, v35, v60
	ds_bpermute_b32 v60, v31, v35
	s_waitcnt lgkmcnt(0)
	v_add_f32_e32 v35, v35, v60
	ds_bpermute_b32 v60, v32, v35
	s_waitcnt lgkmcnt(0)
	v_add_f32_e32 v35, v35, v60
	ds_bpermute_b32 v60, v33, v35
	s_waitcnt lgkmcnt(0)
	v_add_f32_e32 v35, v35, v60
	v_fmamk_f32 v35, v35, 0x3a000000, v13
	v_mul_f32_e32 v60, 0x4f800000, v35
	v_cmp_gt_f32_e32 vcc, s0, v35
	s_nop 1
	v_cndmask_b32_e32 v35, v35, v60, vcc
	v_sqrt_f32_e32 v60, v35
	s_nop 0
	v_add_u32_e32 v61, -1, v60
	v_add_u32_e32 v62, 1, v60
	v_fma_f32 v63, -v61, v60, v35
	v_fma_f32 v64, -v62, v60, v35
	v_cmp_ge_f32_e64 s[4:5], 0, v63
	s_nop 1
	v_cndmask_b32_e64 v60, v60, v61, s[4:5]
	v_cmp_lt_f32_e64 s[4:5], 0, v64
	s_nop 1
	v_cndmask_b32_e64 v60, v60, v62, s[4:5]
	v_mul_f32_e32 v61, 0x37800000, v60
	v_cndmask_b32_e32 v60, v60, v61, vcc
	v_cmp_class_f32_e32 vcc, v35, v34
	s_nop 1
	v_cndmask_b32_e32 v35, v60, v35, vcc
	v_div_scale_f32 v60, s[4:5], v35, v35, 1.0
	v_rcp_f32_e32 v62, v60
	v_div_scale_f32 v61, vcc, 1.0, v35, 1.0
	v_fma_f32 v63, -v60, v62, 1.0
	v_fmac_f32_e32 v62, v63, v62
	v_mul_f32_e32 v63, v61, v62
	v_fma_f32 v64, -v60, v63, v61
	v_fmac_f32_e32 v63, v64, v62
	v_fma_f32 v60, -v60, v63, v61
	v_div_fmas_f32 v60, v60, v62, v63
	v_div_fixup_f32 v60, v60, v35, 1.0
	v_pk_mul_f32 v[36:37], v[36:37], v[60:61] op_sel_hi:[1,0]
	v_pk_mul_f32 v[38:39], v[38:39], v[60:61] op_sel_hi:[1,0]
	v_pk_mul_f32 v[36:37], v[100:101], v[36:37]
	v_pk_mul_f32 v[38:39], v[102:103], v[38:39]
	v_cvt_pk_bf16_f32 v36, v36, v37
	s_nop 0
	v_cvt_pk_bf16_f32 v37, v38, v39
	global_store_dwordx2 v[26:27], v[36:37], off
	v_pk_mul_f32 v[40:41], v[40:41], v[60:61] op_sel_hi:[1,0]
	v_pk_mul_f32 v[42:43], v[42:43], v[60:61] op_sel_hi:[1,0]
	v_pk_mul_f32 v[40:41], v[104:105], v[40:41]
	v_pk_mul_f32 v[42:43], v[106:107], v[42:43]
	v_cvt_pk_bf16_f32 v40, v40, v41
	s_nop 0
	v_cvt_pk_bf16_f32 v41, v42, v43
	global_store_dwordx2 v[26:27], v[40:41], off offset:512
	v_pk_mul_f32 v[44:45], v[44:45], v[60:61] op_sel_hi:[1,0]
	v_pk_mul_f32 v[46:47], v[46:47], v[60:61] op_sel_hi:[1,0]
	v_pk_mul_f32 v[44:45], v[108:109], v[44:45]
	v_pk_mul_f32 v[46:47], v[110:111], v[46:47]
	v_cvt_pk_bf16_f32 v44, v44, v45
	s_nop 0
	v_cvt_pk_bf16_f32 v45, v46, v47
	global_store_dwordx2 v[26:27], v[44:45], off offset:1024
	v_pk_mul_f32 v[48:49], v[48:49], v[60:61] op_sel_hi:[1,0]
	v_pk_mul_f32 v[50:51], v[50:51], v[60:61] op_sel_hi:[1,0]
	v_pk_mul_f32 v[48:49], v[112:113], v[48:49]
	v_pk_mul_f32 v[50:51], v[114:115], v[50:51]
	v_cvt_pk_bf16_f32 v48, v48, v49
	s_nop 0
	v_cvt_pk_bf16_f32 v49, v50, v51
	global_store_dwordx2 v[26:27], v[48:49], off offset:1536
	v_pk_mul_f32 v[52:53], v[52:53], v[60:61] op_sel_hi:[1,0]
	v_pk_mul_f32 v[54:55], v[54:55], v[60:61] op_sel_hi:[1,0]
	v_pk_mul_f32 v[52:53], v[116:117], v[52:53]
	v_pk_mul_f32 v[54:55], v[118:119], v[54:55]
	v_cvt_pk_bf16_f32 v52, v52, v53
	s_nop 0
	v_cvt_pk_bf16_f32 v53, v54, v55
	global_store_dwordx2 v[26:27], v[52:53], off offset:2048
	v_pk_mul_f32 v[8:9], v[8:9], v[60:61] op_sel_hi:[1,0]
	v_pk_mul_f32 v[10:11], v[10:11], v[60:61] op_sel_hi:[1,0]
	v_pk_mul_f32 v[8:9], v[120:121], v[8:9]
	v_pk_mul_f32 v[10:11], v[122:123], v[10:11]
	v_cvt_pk_bf16_f32 v8, v8, v9
	s_nop 0
	v_cvt_pk_bf16_f32 v9, v10, v11
	global_store_dwordx2 v[26:27], v[8:9], off offset:2560
	v_pk_mul_f32 v[4:5], v[4:5], v[60:61] op_sel_hi:[1,0]
	v_pk_mul_f32 v[6:7], v[6:7], v[60:61] op_sel_hi:[1,0]
	v_pk_mul_f32 v[4:5], v[124:125], v[4:5]
	v_pk_mul_f32 v[6:7], v[126:127], v[6:7]
	v_cvt_pk_bf16_f32 v4, v4, v5
	s_nop 0
	v_cvt_pk_bf16_f32 v5, v6, v7
	global_store_dwordx2 v[26:27], v[4:5], off offset:3072
	v_pk_mul_f32 v[0:1], v[0:1], v[60:61] op_sel_hi:[1,0]
	v_pk_mul_f32 v[2:3], v[2:3], v[60:61] op_sel_hi:[1,0]
	v_pk_mul_f32 v[0:1], v[128:129], v[0:1]
	v_pk_mul_f32 v[2:3], v[130:131], v[2:3]
	v_cvt_pk_bf16_f32 v0, v0, v1
	s_nop 0
	v_cvt_pk_bf16_f32 v1, v2, v3
	global_store_dwordx2 v[26:27], v[0:1], off offset:3584
	v_lshl_add_u64 v[26:27], v[26:27], 0, s[10:11]
	s_andn2_b64 exec, exec, s[14:15]
	s_cbranch_execnz .LBB0_315
; __device__ __forceinline__ unsigned xb_ld(unsigned* p)              { return __hip_atomic_load(p, __ATOMIC_RELAXED, __HIP_MEMORY_SCOPE_AGENT); }
; __device__ __forceinline__ void xcd_barrier_complete(unsigned* bar, unsigned x, unsigned& nloc, unsigned& nx) {
;     const unsigned G = gridDim.x * gridDim.y * gridDim.z;
;     unsigned sum, cnt, mine, sp = 0u;
;     for (;;) {
;         sum = 0u; cnt = 0u; mine = 0u;
; #pragma unroll
;         for (unsigned j = 0; j < 16; ++j) { const unsigned c = xb_ld(&bar[XB_XCNT(j)]); sum += c; cnt += (c > 0u) ? 1u : 0u; mine = (j == x) ? c : mine; }
; __device__ __forceinline__ void xcd_barrier(const XcdBarrier& b) {
;     asm volatile("s_waitcnt vmcnt(0)" ::: "memory");
;     __syncthreads();
;     if (threadIdx.x == 0) {
;         unsigned* bar = b.bar;
;         __builtin_amdgcn_s_waitcnt(0);
;         unsigned nloc = b.st[0], nx = b.st[1];
;         if (nloc == 0u) { xcd_barrier_complete(bar, b.x, nloc, nx); b.st[0] = nloc; b.st[1] = nx; }
.Lmy_rms3x_1:
.LBB0_316:
	s_or_b64 exec, exec, s[6:7]
	s_waitcnt vmcnt(0)
	s_barrier
	s_mov_b64 s[4:5], exec
	v_readlane_b32 s0, v248, 20
	v_readlane_b32 s1, v248, 21
	s_and_b64 s[0:1], s[4:5], s[0:1]
	s_mov_b64 exec, s[0:1]
	s_cbranch_execz .LBB0_368
	s_add_i32 s0, 0, 0x22000
	v_mov_b32_e32 v0, s0
	s_waitcnt vmcnt(0) expcnt(0) lgkmcnt(0)
	ds_read_b32 v2, v0
	s_add_i32 s0, 0, 0x22004
	v_mov_b32_e32 v0, s0
	ds_read_b32 v0, v0
	s_waitcnt lgkmcnt(1)
	v_cmp_ne_u32_e32 vcc, 0, v2
	s_cbranch_vccnz .LBB0_332
	v_readlane_b32 s0, v248, 0
	v_readlane_b32 s1, v248, 1
	s_load_dword s1, s[0:1], 0x14
	s_mov_b32 s0, 1
	v_mov_b32_e32 v16, 0
	s_waitcnt lgkmcnt(0)
	s_lshr_b32 s8, s1, 16
	s_and_b32 s1, s1, 0xffff
	s_cmp_lg_u32 s1, 0
	s_cselect_b64 s[6:7], -1, 0
	s_cmp_lg_u64 s[6:7], 0
	s_addc_u32 s1, s69, 0
	s_cmp_lg_u32 s8, 0
	s_cselect_b64 s[6:7], -1, 0
	s_cmp_lg_u64 s[6:7], 0
	s_mul_i32 s1, s1, s68
	s_addc_u32 s6, s94, 0
	s_mul_i32 s1, s1, s6
	s_add_u32 s6, s30, 0x3e150a00
	s_addc_u32 s7, s31, 0
	s_add_u32 s8, s30, 0x3e150c00
	s_addc_u32 s9, s31, 0
	s_add_u32 s10, s30, 0x3e150d00
	s_addc_u32 s11, s31, 0
	s_add_u32 s14, s30, 0x3e150e00
	s_addc_u32 s15, s31, 0
	s_add_u32 s16, s30, 0x3e150f00
	s_addc_u32 s17, s31, 0
	s_add_u32 s18, s30, 0x3e151000
	s_addc_u32 s19, s31, 0
	s_add_u32 s20, s30, 0x3e151100
	s_addc_u32 s21, s31, 0
	s_add_u32 s22, s30, 0x3e151200
	s_addc_u32 s23, s31, 0
	s_add_u32 s24, s30, 0x3e151300
	s_addc_u32 s25, s31, 0
	s_add_u32 s36, s30, 0x3e151400
	s_addc_u32 s37, s31, 0
	s_add_u32 s38, s30, 0x3e151500
	s_addc_u32 s39, s31, 0
	s_add_u32 s52, s30, 0x3e151600
	s_addc_u32 s53, s31, 0
	s_add_u32 s58, s30, 0x3e151700
	s_addc_u32 s59, s31, 0
	s_add_u32 s64, s30, 0x3e151800
	s_addc_u32 s65, s31, 0
	s_add_u32 s66, s30, 0x3e151900
	s_addc_u32 s67, s31, 0
	s_add_u32 s80, s30, 0x3e151a00
	s_addc_u32 s81, s31, 0
	s_add_u32 s82, s30, 0x3e151b00
	s_addc_u32 s83, s31, 0
	s_branch .LBB0_320

; __device__ __forceinline__ int opaque_tid() { int t = threadIdx.x; asm volatile("" : "+v"(t)); return t; }
; __device__ __forceinline__ void st_bf4(bf16_t* p, const f32x4 v) { u32x2 w; w.x = cvt_pk_bf16(v[0], v[1]); w.y = cvt_pk_bf16(v[2], v[3]); *(u32x2*)p = w; }
; template <bool F32OUT>
; __device__ __forceinline__ void rmsnorm_rows(const float* x, const float* w, bf16_t* outb, float* outf) {
;     const int tid_ = opaque_tid(); const int lane = tid_ & 63, gw = blockIdx.x * 8 + (tid_ >> 6), nw = gridDim.x * 8;
;     for (int row = gw; row < T_; row += nw) {
;         const float* xr = x + (size_t)row * D_; f32x4 v[8]; float ss = 0.f;
; #pragma unroll
;         for (int i = 0; i < 8; ++i) { v[i] = *(const f32x4*)(xr + i * 256 + lane * 4); ss += v[i][0] * v[i][0] + v[i][1] * v[i][1] + v[i][2] * v[i][2] + v[i][3] * v[i][3]; }
;         ss = wave_sum(ss);
;         const float rstd = 1.0f / sqrtf(ss * (1.0f / D_) + 1e-6f);
; #pragma unroll
;         for (int i = 0; i < 8; ++i) { const f32x4 wv = *(const f32x4*)(w + i * 256 + lane * 4); const f32x4 y = v[i] * rstd * wv;
;             if (F32OUT) *(f32x4*)(outf + (size_t)row * D_ + i * 256 + lane * 4) = y; else st_bf4(outb + (size_t)row * D_ + i * 256 + lane * 4, y); }
.LBB0_2025:
	s_or_b64 exec, exec, s[6:7]
	s_waitcnt lgkmcnt(0)
	v_mov_b32_e32 v0, v192
	s_barrier
	s_mov_b32 s0, 0x8000
	v_mov_b32_e32 v0, v192
	s_nop 0
	v_ashrrev_i32_e32 v1, 6, v0
	v_add_u32_e32 v12, s92, v1
	v_cmp_gt_i32_e32 vcc, s0, v12
	s_and_saveexec_b64 s[8:9], vcc
	s_cbranch_execz .LBB0_2028
	v_mbcnt_hi_u32_b32 v1, -1, v193
	v_and_b32_e32 v2, 64, v1
	v_add_u32_e32 v2, 64, v2
	v_xor_b32_e32 v3, 32, v1
	v_cmp_lt_i32_e32 vcc, v3, v2
	s_mov_b64 s[0:1], 0x2000
	v_ashrrev_i32_e32 v13, 31, v12
	v_cndmask_b32_e32 v3, v1, v3, vcc
	v_lshlrev_b32_e32 v28, 2, v3
	v_xor_b32_e32 v3, 16, v1
	v_cmp_lt_i32_e32 vcc, v3, v2
	v_and_b32_e32 v4, 63, v0
	s_ashr_i32 s43, s42, 31
	v_cndmask_b32_e32 v3, v1, v3, vcc
	v_lshlrev_b32_e32 v29, 2, v3
	v_xor_b32_e32 v3, 8, v1
	v_cmp_lt_i32_e32 vcc, v3, v2
	s_lshl_b64 s[10:11], s[42:43], 13
	s_lshl_b64 s[12:13], s[42:43], 12
	v_cndmask_b32_e32 v3, v1, v3, vcc
	v_lshlrev_b32_e32 v30, 2, v3
	v_xor_b32_e32 v3, 4, v1
	v_cmp_lt_i32_e32 vcc, v3, v2
	s_mov_b64 s[14:15], 0
	v_mov_b32_e32 v34, 0x260
	v_cndmask_b32_e32 v3, v1, v3, vcc
	v_lshlrev_b32_e32 v31, 2, v3
	v_xor_b32_e32 v3, 2, v1
	v_cmp_lt_i32_e32 vcc, v3, v2
	s_nop 1
	v_cndmask_b32_e32 v3, v1, v3, vcc
	v_lshlrev_b32_e32 v32, 2, v3
	v_xor_b32_e32 v3, 1, v1
	v_cmp_lt_i32_e32 vcc, v3, v2
	s_nop 1
	v_cndmask_b32_e32 v1, v1, v3, vcc
	v_lshlrev_b32_e32 v33, 2, v1
	v_lshlrev_b32_e32 v1, 4, v0
	v_and_b32_e32 v2, 0x3f0, v1
	v_mov_b32_e32 v3, 0
	v_lshl_add_u64 v[2:3], s[40:41], 0, v[2:3]
	v_lshl_add_u64 v[14:15], v[2:3], 0, s[0:1]
	s_mov_b64 s[0:1], 0x3000
	v_lshl_add_u64 v[16:17], v[2:3], 0, s[0:1]
	s_mov_b64 s[0:1], 0x3400
	v_lshl_add_u64 v[18:19], v[2:3], 0, s[0:1]
	s_mov_b64 s[0:1], 0x3800
	v_lshl_add_u64 v[20:21], v[2:3], 0, s[0:1]
	s_mov_b64 s[0:1], 0x3c00
	v_lshl_add_u64 v[22:23], v[2:3], 0, s[0:1]
	v_lshlrev_b64 v[2:3], 13, v[12:13]
	v_lshl_or_b32 v2, v4, 4, v2
	v_lshl_add_u64 v[0:1], s[28:29], 0, v[2:3]
	s_mov_b64 s[0:1], 0x1000
	v_lshl_add_u64 v[24:25], v[0:1], 0, s[0:1]
	v_lshlrev_b64 v[0:1], 12, v[12:13]
	v_lshl_or_b32 v0, v4, 3, v0
	v_lshl_add_u64 v[0:1], s[30:31], 0, v[0:1]
	s_mov_b64 s[0:1], 0x15550800
	v_lshl_add_u64 v[26:27], v[0:1], 0, s[0:1]
	v_mov_b32_e32 v13, 0x358637bd
	s_mov_b32 s0, 0xf800000
	s_movk_i32 s1, 0x7fff
	global_load_dwordx4 v[100:103], v[14:15], off
	global_load_dwordx4 v[104:107], v[14:15], off offset:1024
	global_load_dwordx4 v[108:111], v[14:15], off offset:2048
	global_load_dwordx4 v[112:115], v[14:15], off offset:3072
	global_load_dwordx4 v[116:119], v[16:17], off
	global_load_dwordx4 v[120:123], v[18:19], off
	global_load_dwordx4 v[124:127], v[20:21], off
	global_load_dwordx4 v[128:131], v[22:23], off
	global_load_dwordx4 v[196:199], v[24:25], off offset:-4096
	global_load_dwordx4 v[200:203], v[24:25], off offset:-3072
	global_load_dwordx4 v[204:207], v[24:25], off offset:-2048
	global_load_dwordx4 v[208:211], v[24:25], off offset:-1024
	global_load_dwordx4 v[212:215], v[24:25], off
	global_load_dwordx4 v[216:219], v[24:25], off offset:1024
	global_load_dwordx4 v[220:223], v[24:25], off offset:2048
	global_load_dwordx4 v[224:227], v[24:25], off offset:3072
	v_add_u32_e32 v12, s42, v12
	v_lshl_add_u64 v[24:25], v[24:25], 0, s[10:11]
	v_cmp_lt_i32_e32 vcc, s1, v12
	s_mov_b64 s[88:89], vcc
	s_mov_b64 s[86:87], exec
	s_andn2_b64 exec, exec, s[88:89]
	global_load_dwordx4 v[164:167], v[24:25], off offset:-4096
	global_load_dwordx4 v[168:171], v[24:25], off offset:-3072
	global_load_dwordx4 v[172:175], v[24:25], off offset:-2048
	global_load_dwordx4 v[176:179], v[24:25], off offset:-1024
	global_load_dwordx4 v[180:183], v[24:25], off
	global_load_dwordx4 v[184:187], v[24:25], off offset:1024
	global_load_dwordx4 v[188:191], v[24:25], off offset:2048
	global_load_dwordx4 v[228:231], v[24:25], off offset:3072
	s_mov_b64 exec, s[86:87]
	v_add_u32_e32 v12, s42, v12
	v_lshl_add_u64 v[24:25], v[24:25], 0, s[10:11]
	s_waitcnt vmcnt(0)
.LBB0_2027:
	s_waitcnt vmcnt(16)
	v_mov_b32_e32 v36, v196
	v_mov_b32_e32 v37, v197
	v_mov_b32_e32 v38, v198
	v_mov_b32_e32 v39, v199
	v_mov_b32_e32 v40, v200
	v_mov_b32_e32 v41, v201
	v_mov_b32_e32 v42, v202
	v_mov_b32_e32 v43, v203
	v_mov_b32_e32 v44, v204
	v_mov_b32_e32 v45, v205
	v_mov_b32_e32 v46, v206
	v_mov_b32_e32 v47, v207
	v_mov_b32_e32 v48, v208
	v_mov_b32_e32 v49, v209
	v_mov_b32_e32 v50, v210
	v_mov_b32_e32 v51, v211
	v_mov_b32_e32 v52, v212
	v_mov_b32_e32 v53, v213
	v_mov_b32_e32 v54, v214
	v_mov_b32_e32 v55, v215
	v_mov_b32_e32 v8, v216
	v_mov_b32_e32 v9, v217
	v_mov_b32_e32 v10, v218
	v_mov_b32_e32 v11, v219
	v_mov_b32_e32 v4, v220
	v_mov_b32_e32 v5, v221
	v_mov_b32_e32 v6, v222
	v_mov_b32_e32 v7, v223
	v_mov_b32_e32 v0, v224
	v_mov_b32_e32 v1, v225
	v_mov_b32_e32 v2, v226
	v_mov_b32_e32 v3, v227
	s_or_b64 s[14:15], s[88:89], s[14:15]
	v_cmp_lt_i32_e32 vcc, s1, v12
	s_or_b64 s[88:89], vcc, s[88:89]
	s_mov_b64 s[86:87], exec
	s_andn2_b64 exec, exec, s[88:89]
	global_load_dwordx4 v[196:199], v[24:25], off offset:-4096
	global_load_dwordx4 v[200:203], v[24:25], off offset:-3072
	global_load_dwordx4 v[204:207], v[24:25], off offset:-2048
	global_load_dwordx4 v[208:211], v[24:25], off offset:-1024
	global_load_dwordx4 v[212:215], v[24:25], off
	global_load_dwordx4 v[216:219], v[24:25], off offset:1024
	global_load_dwordx4 v[220:223], v[24:25], off offset:2048
	global_load_dwordx4 v[224:227], v[24:25], off offset:3072
	s_mov_b64 exec, s[86:87]
	v_add_u32_e32 v12, s42, v12
	v_lshl_add_u64 v[24:25], v[24:25], 0, s[10:11]
	v_mul_f32_e32 v35, v37, v37
	v_mul_f32_e32 v68, v41, v41
	v_mul_f32_e32 v69, v45, v45
	v_fmac_f32_e32 v35, v36, v36
	v_fmac_f32_e32 v68, v40, v40
	v_mul_f32_e32 v70, v49, v49
	v_fmac_f32_e32 v69, v44, v44
	v_fmac_f32_e32 v35, v38, v38
	v_fmac_f32_e32 v68, v42, v42
	v_mul_f32_e32 v71, v53, v53
	v_fmac_f32_e32 v70, v48, v48
	v_fmac_f32_e32 v69, v46, v46
	v_fmac_f32_e32 v35, v39, v39
	v_fmac_f32_e32 v68, v43, v43
	v_mul_f32_e32 v72, v9, v9
	v_mov_b32_e32 v62, v5
	v_mov_b32_e32 v63, v1
	v_fmac_f32_e32 v71, v52, v52
	v_fmac_f32_e32 v70, v50, v50
	v_fmac_f32_e32 v69, v47, v47
	v_add_f32_e32 v35, v35, v68
	v_mov_b32_e32 v60, v4
	v_mov_b32_e32 v61, v0
	v_fmac_f32_e32 v72, v8, v8
	v_pk_mul_f32 v[62:63], v[62:63], v[62:63]
	v_fmac_f32_e32 v71, v54, v54
	v_fmac_f32_e32 v70, v51, v51
	v_add_f32_e32 v35, v35, v69
	v_mov_b32_e32 v64, v6
	v_mov_b32_e32 v65, v2
	v_fmac_f32_e32 v72, v10, v10
	v_pk_fma_f32 v[60:61], v[60:61], v[60:61], v[62:63]
	v_fmac_f32_e32 v71, v55, v55
	v_add_f32_e32 v35, v35, v70
	v_mov_b32_e32 v66, v7
	v_mov_b32_e32 v67, v3
	v_fmac_f32_e32 v72, v11, v11
	v_pk_fma_f32 v[60:61], v[64:65], v[64:65], v[60:61]
	v_add_f32_e32 v35, v35, v71
	v_pk_fma_f32 v[60:61], v[66:67], v[66:67], v[60:61]
	v_add_f32_e32 v35, v35, v72
	v_add_f32_e32 v35, v35, v60
	v_add_f32_e32 v35, v35, v61
	ds_bpermute_b32 v60, v28, v35
	s_waitcnt lgkmcnt(0)
; __device__ __forceinline__ void st_bf4(bf16_t* p, const f32x4 v) { u32x2 w; w.x = cvt_pk_bf16(v[0], v[1]); w.y = cvt_pk_bf16(v[2], v[3]); *(u32x2*)p = w; }
; template <bool F32OUT>
; __device__ __forceinline__ void rmsnorm_rows(const float* x, const float* w, bf16_t* outb, float* outf) {
;     ...
;         ss = wave_sum(ss);
;         const float rstd = 1.0f / sqrtf(ss * (1.0f / D_) + 1e-6f);
; #pragma unroll
;         for (int i = 0; i < 8; ++i) { const f32x4 wv = *(const f32x4*)(w + i * 256 + lane * 4); const f32x4 y = v[i] * rstd * wv;
;             if (F32OUT) *(f32x4*)(outf + (size_t)row * D_ + i * 256 + lane * 4) = y; else st_bf4(outb + (size_t)row * D_ + i * 256 + lane * 4, y); }
	v_add_f32_e32 v35, v35, v60
	ds_bpermute_b32 v60, v29, v35
	s_waitcnt lgkmcnt(0)
	v_add_f32_e32 v35, v35, v60
	ds_bpermute_b32 v60, v30, v35
	s_waitcnt lgkmcnt(0)
	v_add_f32_e32 v35, v35, v60
	ds_bpermute_b32 v60, v31, v35
	s_waitcnt lgkmcnt(0)
	v_add_f32_e32 v35, v35, v60
	ds_bpermute_b32 v60, v32, v35
	s_waitcnt lgkmcnt(0)
	v_add_f32_e32 v35, v35, v60
	ds_bpermute_b32 v60, v33, v35
	s_waitcnt lgkmcnt(0)
	v_add_f32_e32 v35, v35, v60
	v_fmamk_f32 v35, v35, 0x3a000000, v13
	v_mul_f32_e32 v60, 0x4f800000, v35
	v_cmp_gt_f32_e32 vcc, s0, v35
	s_nop 1
	v_cndmask_b32_e32 v35, v35, v60, vcc
	v_sqrt_f32_e32 v60, v35
	s_nop 0
	v_add_u32_e32 v61, -1, v60
	v_add_u32_e32 v62, 1, v60
	v_fma_f32 v63, -v61, v60, v35
	v_fma_f32 v64, -v62, v60, v35
	v_cmp_ge_f32_e64 s[6:7], 0, v63
	s_nop 1
	v_cndmask_b32_e64 v60, v60, v61, s[6:7]
	v_cmp_lt_f32_e64 s[6:7], 0, v64
	s_nop 1
	v_cndmask_b32_e64 v60, v60, v62, s[6:7]
	v_mul_f32_e32 v61, 0x37800000, v60
	v_cndmask_b32_e32 v60, v60, v61, vcc
	v_cmp_class_f32_e32 vcc, v35, v34
	s_nop 1
	v_cndmask_b32_e32 v35, v60, v35, vcc
	v_div_scale_f32 v60, s[6:7], v35, v35, 1.0
	v_rcp_f32_e32 v62, v60
	v_div_scale_f32 v61, vcc, 1.0, v35, 1.0
	v_fma_f32 v63, -v60, v62, 1.0
	v_fmac_f32_e32 v62, v63, v62
	v_mul_f32_e32 v63, v61, v62
	v_fma_f32 v64, -v60, v63, v61
	v_fmac_f32_e32 v63, v64, v62
	v_fma_f32 v60, -v60, v63, v61
	v_div_fmas_f32 v60, v60, v62, v63
	v_div_fixup_f32 v60, v60, v35, 1.0
	v_pk_mul_f32 v[36:37], v[36:37], v[60:61] op_sel_hi:[1,0]
	v_pk_mul_f32 v[38:39], v[38:39], v[60:61] op_sel_hi:[1,0]
	v_pk_mul_f32 v[36:37], v[100:101], v[36:37]
	v_pk_mul_f32 v[38:39], v[102:103], v[38:39]
	v_cvt_pk_bf16_f32 v36, v36, v37
	s_nop 0
	v_cvt_pk_bf16_f32 v37, v38, v39
	global_store_dwordx2 v[26:27], v[36:37], off
	v_pk_mul_f32 v[40:41], v[40:41], v[60:61] op_sel_hi:[1,0]
	v_pk_mul_f32 v[42:43], v[42:43], v[60:61] op_sel_hi:[1,0]
	v_pk_mul_f32 v[40:41], v[104:105], v[40:41]
	v_pk_mul_f32 v[42:43], v[106:107], v[42:43]
	v_cvt_pk_bf16_f32 v40, v40, v41
	s_nop 0
	v_cvt_pk_bf16_f32 v41, v42, v43
	global_store_dwordx2 v[26:27], v[40:41], off offset:512
	v_pk_mul_f32 v[44:45], v[44:45], v[60:61] op_sel_hi:[1,0]
	v_pk_mul_f32 v[46:47], v[46:47], v[60:61] op_sel_hi:[1,0]
	v_pk_mul_f32 v[44:45], v[108:109], v[44:45]
	v_pk_mul_f32 v[46:47], v[110:111], v[46:47]
	v_cvt_pk_bf16_f32 v44, v44, v45
	s_nop 0
	v_cvt_pk_bf16_f32 v45, v46, v47
	global_store_dwordx2 v[26:27], v[44:45], off offset:1024
	v_pk_mul_f32 v[48:49], v[48:49], v[60:61] op_sel_hi:[1,0]
	v_pk_mul_f32 v[50:51], v[50:51], v[60:61] op_sel_hi:[1,0]
	v_pk_mul_f32 v[48:49], v[112:113], v[48:49]
	v_pk_mul_f32 v[50:51], v[114:115], v[50:51]
	v_cvt_pk_bf16_f32 v48, v48, v49
	s_nop 0
	v_cvt_pk_bf16_f32 v49, v50, v51
	global_store_dwordx2 v[26:27], v[48:49], off offset:1536
	v_pk_mul_f32 v[52:53], v[52:53], v[60:61] op_sel_hi:[1,0]
	v_pk_mul_f32 v[54:55], v[54:55], v[60:61] op_sel_hi:[1,0]
	v_pk_mul_f32 v[52:53], v[116:117], v[52:53]
	v_pk_mul_f32 v[54:55], v[118:119], v[54:55]
	v_cvt_pk_bf16_f32 v52, v52, v53
	s_nop 0
	v_cvt_pk_bf16_f32 v53, v54, v55
	global_store_dwordx2 v[26:27], v[52:53], off offset:2048
	v_pk_mul_f32 v[8:9], v[8:9], v[60:61] op_sel_hi:[1,0]
	v_pk_mul_f32 v[10:11], v[10:11], v[60:61] op_sel_hi:[1,0]
	v_pk_mul_f32 v[8:9], v[120:121], v[8:9]
	v_pk_mul_f32 v[10:11], v[122:123], v[10:11]
	v_cvt_pk_bf16_f32 v8, v8, v9
	s_nop 0
	v_cvt_pk_bf16_f32 v9, v10, v11
	global_store_dwordx2 v[26:27], v[8:9], off offset:2560
	v_pk_mul_f32 v[4:5], v[4:5], v[60:61] op_sel_hi:[1,0]
	v_pk_mul_f32 v[6:7], v[6:7], v[60:61] op_sel_hi:[1,0]
	v_pk_mul_f32 v[4:5], v[124:125], v[4:5]
	v_pk_mul_f32 v[6:7], v[126:127], v[6:7]
	v_cvt_pk_bf16_f32 v4, v4, v5
	s_nop 0
	v_cvt_pk_bf16_f32 v5, v6, v7
	global_store_dwordx2 v[26:27], v[4:5], off offset:3072
	v_pk_mul_f32 v[0:1], v[0:1], v[60:61] op_sel_hi:[1,0]
	v_pk_mul_f32 v[2:3], v[2:3], v[60:61] op_sel_hi:[1,0]
	v_pk_mul_f32 v[0:1], v[128:129], v[0:1]
	v_pk_mul_f32 v[2:3], v[130:131], v[2:3]
	v_cvt_pk_bf16_f32 v0, v0, v1
	s_nop 0
	v_cvt_pk_bf16_f32 v1, v2, v3
	global_store_dwordx2 v[26:27], v[0:1], off offset:3584
	v_lshl_add_u64 v[26:27], v[26:27], 0, s[12:13]
	s_andn2_b64 exec, exec, s[14:15]
	s_cbranch_execz .Lmy_rms3x_2
	s_waitcnt vmcnt(16)
	v_mov_b32_e32 v36, v164
	v_mov_b32_e32 v37, v165
	v_mov_b32_e32 v38, v166
	v_mov_b32_e32 v39, v167
	v_mov_b32_e32 v40, v168
	v_mov_b32_e32 v41, v169
	v_mov_b32_e32 v42, v170
	v_mov_b32_e32 v43, v171
	v_mov_b32_e32 v44, v172
	v_mov_b32_e32 v45, v173
	v_mov_b32_e32 v46, v174
	v_mov_b32_e32 v47, v175
	v_mov_b32_e32 v48, v176
	v_mov_b32_e32 v49, v177
	v_mov_b32_e32 v50, v178
	v_mov_b32_e32 v51, v179
	v_mov_b32_e32 v52, v180
	v_mov_b32_e32 v53, v181
	v_mov_b32_e32 v54, v182
	v_mov_b32_e32 v55, v183
	v_mov_b32_e32 v8, v184
	v_mov_b32_e32 v9, v185
	v_mov_b32_e32 v10, v186
	v_mov_b32_e32 v11, v187
	v_mov_b32_e32 v4, v188
	v_mov_b32_e32 v5, v189
	v_mov_b32_e32 v6, v190
	v_mov_b32_e32 v7, v191
	v_mov_b32_e32 v0, v228
	v_mov_b32_e32 v1, v229
	v_mov_b32_e32 v2, v230
	v_mov_b32_e32 v3, v231
	s_or_b64 s[14:15], s[88:89], s[14:15]
	v_cmp_lt_i32_e32 vcc, s1, v12
	s_or_b64 s[88:89], vcc, s[88:89]
	s_mov_b64 s[86:87], exec
	s_andn2_b64 exec, exec, s[88:89]
	global_load_dwordx4 v[164:167], v[24:25], off offset:-4096
	global_load_dwordx4 v[168:171], v[24:25], off offset:-3072
	global_load_dwordx4 v[172:175], v[24:25], off offset:-2048
	global_load_dwordx4 v[176:179], v[24:25], off offset:-1024
	global_load_dwordx4 v[180:183], v[24:25], off
	global_load_dwordx4 v[184:187], v[24:25], off offset:1024
	global_load_dwordx4 v[188:191], v[24:25], off offset:2048
	global_load_dwordx4 v[228:231], v[24:25], off offset:3072
; __device__ __forceinline__ void st_bf4(bf16_t* p, const f32x4 v) { u32x2 w; w.x = cvt_pk_bf16(v[0], v[1]); w.y = cvt_pk_bf16(v[2], v[3]); *(u32x2*)p = w; }
; template <bool F32OUT>
; __device__ __forceinline__ void rmsnorm_rows(const float* x, const float* w, bf16_t* outb, float* outf) {
;     ...
;         const float* xr = x + (size_t)row * D_; f32x4 v[8]; float ss = 0.f;
; #pragma unroll
;         for (int i = 0; i < 8; ++i) { v[i] = *(const f32x4*)(xr + i * 256 + lane * 4); ss += v[i][0] * v[i][0] + v[i][1] * v[i][1] + v[i][2] * v[i][2] + v[i][3] * v[i][3]; }
;         ss = wave_sum(ss);
;         const float rstd = 1.0f / sqrtf(ss * (1.0f / D_) + 1e-6f);
; #pragma unroll
;         for (int i = 0; i < 8; ++i) { const f32x4 wv = *(const f32x4*)(w + i * 256 + lane * 4); const f32x4 y = v[i] * rstd * wv;
;             if (F32OUT) *(f32x4*)(outf + (size_t)row * D_ + i * 256 + lane * 4) = y; else st_bf4(outb + (size_t)row * D_ + i * 256 + lane * 4, y); }
	s_mov_b64 exec, s[86:87]
	v_add_u32_e32 v12, s42, v12
	v_lshl_add_u64 v[24:25], v[24:25], 0, s[10:11]
	v_mul_f32_e32 v35, v37, v37
	v_mul_f32_e32 v68, v41, v41
	v_mul_f32_e32 v69, v45, v45
	v_fmac_f32_e32 v35, v36, v36
	v_fmac_f32_e32 v68, v40, v40
	v_mul_f32_e32 v70, v49, v49
	v_fmac_f32_e32 v69, v44, v44
	v_fmac_f32_e32 v35, v38, v38
	v_fmac_f32_e32 v68, v42, v42
	v_mul_f32_e32 v71, v53, v53
	v_fmac_f32_e32 v70, v48, v48
	v_fmac_f32_e32 v69, v46, v46
	v_fmac_f32_e32 v35, v39, v39
	v_fmac_f32_e32 v68, v43, v43
	v_mul_f32_e32 v72, v9, v9
	v_mov_b32_e32 v62, v5
	v_mov_b32_e32 v63, v1
	v_fmac_f32_e32 v71, v52, v52
	v_fmac_f32_e32 v70, v50, v50
	v_fmac_f32_e32 v69, v47, v47
	v_add_f32_e32 v35, v35, v68
	v_mov_b32_e32 v60, v4
	v_mov_b32_e32 v61, v0
	v_fmac_f32_e32 v72, v8, v8
	v_pk_mul_f32 v[62:63], v[62:63], v[62:63]
	v_fmac_f32_e32 v71, v54, v54
	v_fmac_f32_e32 v70, v51, v51
	v_add_f32_e32 v35, v35, v69
	v_mov_b32_e32 v64, v6
	v_mov_b32_e32 v65, v2
	v_fmac_f32_e32 v72, v10, v10
	v_pk_fma_f32 v[60:61], v[60:61], v[60:61], v[62:63]
	v_fmac_f32_e32 v71, v55, v55
	v_add_f32_e32 v35, v35, v70
	v_mov_b32_e32 v66, v7
	v_mov_b32_e32 v67, v3
	v_fmac_f32_e32 v72, v11, v11
	v_pk_fma_f32 v[60:61], v[64:65], v[64:65], v[60:61]
	v_add_f32_e32 v35, v35, v71
	v_pk_fma_f32 v[60:61], v[66:67], v[66:67], v[60:61]
	v_add_f32_e32 v35, v35, v72
	v_add_f32_e32 v35, v35, v60
	v_add_f32_e32 v35, v35, v61
	ds_bpermute_b32 v60, v28, v35
	s_waitcnt lgkmcnt(0)
	v_add_f32_e32 v35, v35, v60
	ds_bpermute_b32 v60, v29, v35
	s_waitcnt lgkmcnt(0)
	v_add_f32_e32 v35, v35, v60
	ds_bpermute_b32 v60, v30, v35
	s_waitcnt lgkmcnt(0)
	v_add_f32_e32 v35, v35, v60
	ds_bpermute_b32 v60, v31, v35
	s_waitcnt lgkmcnt(0)
	v_add_f32_e32 v35, v35, v60
	ds_bpermute_b32 v60, v32, v35
	s_waitcnt lgkmcnt(0)
	v_add_f32_e32 v35, v35, v60
	ds_bpermute_b32 v60, v33, v35
	s_waitcnt lgkmcnt(0)
	v_add_f32_e32 v35, v35, v60
	v_fmamk_f32 v35, v35, 0x3a000000, v13
	v_mul_f32_e32 v60, 0x4f800000, v35
	v_cmp_gt_f32_e32 vcc, s0, v35
	s_nop 1
	v_cndmask_b32_e32 v35, v35, v60, vcc
	v_sqrt_f32_e32 v60, v35
	s_nop 0
	v_add_u32_e32 v61, -1, v60
	v_add_u32_e32 v62, 1, v60
	v_fma_f32 v63, -v61, v60, v35
	v_fma_f32 v64, -v62, v60, v35
	v_cmp_ge_f32_e64 s[6:7], 0, v63
	s_nop 1
	v_cndmask_b32_e64 v60, v60, v61, s[6:7]
	v_cmp_lt_f32_e64 s[6:7], 0, v64
	s_nop 1
	v_cndmask_b32_e64 v60, v60, v62, s[6:7]
	v_mul_f32_e32 v61, 0x37800000, v60
	v_cndmask_b32_e32 v60, v60, v61, vcc
	v_cmp_class_f32_e32 vcc, v35, v34
	s_nop 1
	v_cndmask_b32_e32 v35, v60, v35, vcc
	v_div_scale_f32 v60, s[6:7], v35, v35, 1.0
	v_rcp_f32_e32 v62, v60
	v_div_scale_f32 v61, vcc, 1.0, v35, 1.0
	v_fma_f32 v63, -v60, v62, 1.0
	v_fmac_f32_e32 v62, v63, v62
	v_mul_f32_e32 v63, v61, v62
	v_fma_f32 v64, -v60, v63, v61
	v_fmac_f32_e32 v63, v64, v62
	v_fma_f32 v60, -v60, v63, v61
	v_div_fmas_f32 v60, v60, v62, v63
	v_div_fixup_f32 v60, v60, v35, 1.0
	v_pk_mul_f32 v[36:37], v[36:37], v[60:61] op_sel_hi:[1,0]
	v_pk_mul_f32 v[38:39], v[38:39], v[60:61] op_sel_hi:[1,0]
	v_pk_mul_f32 v[36:37], v[100:101], v[36:37]
	v_pk_mul_f32 v[38:39], v[102:103], v[38:39]
	v_cvt_pk_bf16_f32 v36, v36, v37
	s_nop 0
	v_cvt_pk_bf16_f32 v37, v38, v39
	global_store_dwordx2 v[26:27], v[36:37], off
	v_pk_mul_f32 v[40:41], v[40:41], v[60:61] op_sel_hi:[1,0]
	v_pk_mul_f32 v[42:43], v[42:43], v[60:61] op_sel_hi:[1,0]
	v_pk_mul_f32 v[40:41], v[104:105], v[40:41]
	v_pk_mul_f32 v[42:43], v[106:107], v[42:43]
	v_cvt_pk_bf16_f32 v40, v40, v41
	s_nop 0
	v_cvt_pk_bf16_f32 v41, v42, v43
	global_store_dwordx2 v[26:27], v[40:41], off offset:512
	v_pk_mul_f32 v[44:45], v[44:45], v[60:61] op_sel_hi:[1,0]
	v_pk_mul_f32 v[46:47], v[46:47], v[60:61] op_sel_hi:[1,0]
	v_pk_mul_f32 v[44:45], v[108:109], v[44:45]
	v_pk_mul_f32 v[46:47], v[110:111], v[46:47]
	v_cvt_pk_bf16_f32 v44, v44, v45
	s_nop 0
	v_cvt_pk_bf16_f32 v45, v46, v47
	global_store_dwordx2 v[26:27], v[44:45], off offset:1024
	v_pk_mul_f32 v[48:49], v[48:49], v[60:61] op_sel_hi:[1,0]
	v_pk_mul_f32 v[50:51], v[50:51], v[60:61] op_sel_hi:[1,0]
	v_pk_mul_f32 v[48:49], v[112:113], v[48:49]
	v_pk_mul_f32 v[50:51], v[114:115], v[50:51]
	v_cvt_pk_bf16_f32 v48, v48, v49
	s_nop 0
	v_cvt_pk_bf16_f32 v49, v50, v51
	global_store_dwordx2 v[26:27], v[48:49], off offset:1536
	v_pk_mul_f32 v[52:53], v[52:53], v[60:61] op_sel_hi:[1,0]
	v_pk_mul_f32 v[54:55], v[54:55], v[60:61] op_sel_hi:[1,0]
	v_pk_mul_f32 v[52:53], v[116:117], v[52:53]
	v_pk_mul_f32 v[54:55], v[118:119], v[54:55]
	v_cvt_pk_bf16_f32 v52, v52, v53
	s_nop 0
	v_cvt_pk_bf16_f32 v53, v54, v55
	global_store_dwordx2 v[26:27], v[52:53], off offset:2048
	v_pk_mul_f32 v[8:9], v[8:9], v[60:61] op_sel_hi:[1,0]
	v_pk_mul_f32 v[10:11], v[10:11], v[60:61] op_sel_hi:[1,0]
	v_pk_mul_f32 v[8:9], v[120:121], v[8:9]
	v_pk_mul_f32 v[10:11], v[122:123], v[10:11]
	v_cvt_pk_bf16_f32 v8, v8, v9
	s_nop 0
	v_cvt_pk_bf16_f32 v9, v10, v11
	global_store_dwordx2 v[26:27], v[8:9], off offset:2560
	v_pk_mul_f32 v[4:5], v[4:5], v[60:61] op_sel_hi:[1,0]
	v_pk_mul_f32 v[6:7], v[6:7], v[60:61] op_sel_hi:[1,0]
	v_pk_mul_f32 v[4:5], v[124:125], v[4:5]
	v_pk_mul_f32 v[6:7], v[126:127], v[6:7]
	v_cvt_pk_bf16_f32 v4, v4, v5
	s_nop 0
	v_cvt_pk_bf16_f32 v5, v6, v7
	global_store_dwordx2 v[26:27], v[4:5], off offset:3072
	v_pk_mul_f32 v[0:1], v[0:1], v[60:61] op_sel_hi:[1,0]
	v_pk_mul_f32 v[2:3], v[2:3], v[60:61] op_sel_hi:[1,0]
	v_pk_mul_f32 v[0:1], v[128:129], v[0:1]
	v_pk_mul_f32 v[2:3], v[130:131], v[2:3]
	v_cvt_pk_bf16_f32 v0, v0, v1
	s_nop 0
	v_cvt_pk_bf16_f32 v1, v2, v3
	global_store_dwordx2 v[26:27], v[0:1], off offset:3584
	v_lshl_add_u64 v[26:27], v[26:27], 0, s[12:13]
	s_andn2_b64 exec, exec, s[14:15]
	s_cbranch_execnz .LBB0_2027
; __device__ __forceinline__ unsigned xb_ld(unsigned* p)              { return __hip_atomic_load(p, __ATOMIC_RELAXED, __HIP_MEMORY_SCOPE_AGENT); }
; __device__ __forceinline__ void xcd_barrier_complete(unsigned* bar, unsigned x, unsigned& nloc, unsigned& nx) {
;     const unsigned G = gridDim.x * gridDim.y * gridDim.z;
;     unsigned sum, cnt, mine, sp = 0u;
;     for (;;) {
;         sum = 0u; cnt = 0u; mine = 0u;
; #pragma unroll
;         for (unsigned j = 0; j < 16; ++j) { const unsigned c = xb_ld(&bar[XB_XCNT(j)]); sum += c; cnt += (c > 0u) ? 1u : 0u; mine = (j == x) ? c : mine; }
; __device__ __forceinline__ void xcd_barrier(const XcdBarrier& b) {
;     asm volatile("s_waitcnt vmcnt(0)" ::: "memory");
;     __syncthreads();
;     if (threadIdx.x == 0) {
;         unsigned* bar = b.bar;
;         __builtin_amdgcn_s_waitcnt(0);
;         unsigned nloc = b.st[0], nx = b.st[1];
;         if (nloc == 0u) { xcd_barrier_complete(bar, b.x, nloc, nx); b.st[0] = nloc; b.st[1] = nx; }
.Lmy_rms3x_2:
.LBB0_2028:
	s_or_b64 exec, exec, s[8:9]
	s_waitcnt vmcnt(0)
	s_barrier
	s_mov_b64 s[6:7], exec
	v_readlane_b32 s0, v248, 20
	v_readlane_b32 s1, v248, 21
	s_and_b64 s[0:1], s[6:7], s[0:1]
	s_mov_b64 exec, s[0:1]
	s_cbranch_execz .LBB0_2080
	s_add_i32 s0, 0, 0x22000
	v_mov_b32_e32 v0, s0
	s_waitcnt vmcnt(0) expcnt(0) lgkmcnt(0)
	ds_read_b32 v2, v0
	s_add_i32 s0, 0, 0x22004
	v_mov_b32_e32 v0, s0
	ds_read_b32 v0, v0
	s_waitcnt lgkmcnt(1)
	v_cmp_ne_u32_e32 vcc, 0, v2
	s_cbranch_vccnz .LBB0_2044
	v_readlane_b32 s0, v248, 0
	v_readlane_b32 s1, v248, 1
	s_load_dword s1, s[0:1], 0x14
	s_mov_b32 s0, 1
	v_mov_b32_e32 v16, 0
	s_waitcnt lgkmcnt(0)
	s_lshr_b32 s10, s1, 16
	s_and_b32 s1, s1, 0xffff
	s_cmp_lg_u32 s1, 0
	s_cselect_b64 s[8:9], -1, 0
	s_cmp_lg_u64 s[8:9], 0
	s_addc_u32 s1, s69, 0
	s_cmp_lg_u32 s10, 0
	s_cselect_b64 s[8:9], -1, 0
	s_cmp_lg_u64 s[8:9], 0
	s_mul_i32 s1, s1, s68
	s_addc_u32 s8, s94, 0
	s_mul_i32 s1, s1, s8
	s_add_u32 s8, s30, 0x3e150a00
	s_addc_u32 s9, s31, 0
	s_add_u32 s10, s30, 0x3e150c00
	s_addc_u32 s11, s31, 0
	s_add_u32 s12, s30, 0x3e150d00
	s_addc_u32 s13, s31, 0
	s_add_u32 s14, s30, 0x3e150e00
	s_addc_u32 s15, s31, 0
	s_add_u32 s16, s30, 0x3e150f00
	s_addc_u32 s17, s31, 0
	s_add_u32 s18, s30, 0x3e151000
	s_addc_u32 s19, s31, 0
	s_add_u32 s20, s30, 0x3e151100
	s_addc_u32 s21, s31, 0
	s_add_u32 s22, s30, 0x3e151200
	s_addc_u32 s23, s31, 0
	s_add_u32 s24, s30, 0x3e151300
	s_addc_u32 s25, s31, 0
	s_add_u32 s36, s30, 0x3e151400
	s_addc_u32 s37, s31, 0
	s_add_u32 s38, s30, 0x3e151500
	s_addc_u32 s39, s31, 0
	s_add_u32 s56, s30, 0x3e151600
	s_addc_u32 s57, s31, 0
	s_add_u32 s58, s30, 0x3e151700
	s_addc_u32 s59, s31, 0
	s_add_u32 s64, s30, 0x3e151800
	s_addc_u32 s65, s31, 0
	s_add_u32 s66, s30, 0x3e151900
	s_addc_u32 s67, s31, 0
	s_add_u32 s78, s30, 0x3e151a00
	s_addc_u32 s79, s31, 0
	s_add_u32 s80, s30, 0x3e151b00
	s_addc_u32 s81, s31, 0
	s_branch .LBB0_2032

; __device__ __forceinline__ int opaque_tid() { int t = threadIdx.x; asm volatile("" : "+v"(t)); return t; }
; __device__ __forceinline__ void st_bf4(bf16_t* p, const f32x4 v) { u32x2 w; w.x = cvt_pk_bf16(v[0], v[1]); w.y = cvt_pk_bf16(v[2], v[3]); *(u32x2*)p = w; }
; template <bool F32OUT>
; __device__ __forceinline__ void rmsnorm_rows(const float* x, const float* w, bf16_t* outb, float* outf) {
;     const int tid_ = opaque_tid(); const int lane = tid_ & 63, gw = blockIdx.x * 8 + (tid_ >> 6), nw = gridDim.x * 8;
;     for (int row = gw; row < T_; row += nw) {
;         const float* xr = x + (size_t)row * D_; f32x4 v[8]; float ss = 0.f;
; #pragma unroll
;         for (int i = 0; i < 8; ++i) { v[i] = *(const f32x4*)(xr + i * 256 + lane * 4); ss += v[i][0] * v[i][0] + v[i][1] * v[i][1] + v[i][2] * v[i][2] + v[i][3] * v[i][3]; }
;         ss = wave_sum(ss);
;         const float rstd = 1.0f / sqrtf(ss * (1.0f / D_) + 1e-6f);
; #pragma unroll
;         for (int i = 0; i < 8; ++i) { const f32x4 wv = *(const f32x4*)(w + i * 256 + lane * 4); const f32x4 y = v[i] * rstd * wv;
;             if (F32OUT) *(f32x4*)(outf + (size_t)row * D_ + i * 256 + lane * 4) = y; else st_bf4(outb + (size_t)row * D_ + i * 256 + lane * 4, y); }
.LBB0_2224:
	s_or_b64 exec, exec, s[8:9]
	s_waitcnt lgkmcnt(0)
	v_mov_b32_e32 v0, v192
	s_barrier
	s_mov_b32 s0, 0x8000
	v_mov_b32_e32 v0, v192
	s_nop 0
	v_ashrrev_i32_e32 v1, 6, v0
	v_add_u32_e32 v12, s92, v1
	v_cmp_gt_i32_e32 vcc, s0, v12
	s_and_saveexec_b64 s[10:11], vcc
	s_cbranch_execz .LBB0_2227
	v_mbcnt_hi_u32_b32 v1, -1, v193
	v_and_b32_e32 v2, 64, v1
	v_add_u32_e32 v2, 64, v2
	v_xor_b32_e32 v3, 32, v1
	v_cmp_lt_i32_e32 vcc, v3, v2
	s_mov_b64 s[0:1], 0x4000
	v_ashrrev_i32_e32 v13, 31, v12
	v_cndmask_b32_e32 v3, v1, v3, vcc
	v_lshlrev_b32_e32 v28, 2, v3
	v_xor_b32_e32 v3, 16, v1
	v_cmp_lt_i32_e32 vcc, v3, v2
	v_and_b32_e32 v4, 63, v0
	s_ashr_i32 s43, s42, 31
	v_cndmask_b32_e32 v3, v1, v3, vcc
	v_lshlrev_b32_e32 v29, 2, v3
	v_xor_b32_e32 v3, 8, v1
	v_cmp_lt_i32_e32 vcc, v3, v2
	s_lshl_b64 s[12:13], s[42:43], 13
	s_lshl_b64 s[14:15], s[42:43], 12
	v_cndmask_b32_e32 v3, v1, v3, vcc
	v_lshlrev_b32_e32 v30, 2, v3
	v_xor_b32_e32 v3, 4, v1
	v_cmp_lt_i32_e32 vcc, v3, v2
	s_mov_b64 s[16:17], 0
	v_mov_b32_e32 v34, 0x260
	v_cndmask_b32_e32 v3, v1, v3, vcc
	v_lshlrev_b32_e32 v31, 2, v3
	v_xor_b32_e32 v3, 2, v1
	v_cmp_lt_i32_e32 vcc, v3, v2
	s_nop 1
	v_cndmask_b32_e32 v3, v1, v3, vcc
	v_lshlrev_b32_e32 v32, 2, v3
	v_xor_b32_e32 v3, 1, v1
	v_cmp_lt_i32_e32 vcc, v3, v2
	s_nop 1
	v_cndmask_b32_e32 v1, v1, v3, vcc
	v_lshlrev_b32_e32 v33, 2, v1
	v_lshlrev_b32_e32 v1, 4, v0
	v_and_b32_e32 v2, 0x3f0, v1
	v_mov_b32_e32 v3, 0
	v_lshl_add_u64 v[2:3], s[40:41], 0, v[2:3]
	v_lshl_add_u64 v[14:15], v[2:3], 0, s[0:1]
	s_mov_b64 s[0:1], 0x5000
	v_lshl_add_u64 v[16:17], v[2:3], 0, s[0:1]
	s_mov_b64 s[0:1], 0x5400
	v_lshl_add_u64 v[18:19], v[2:3], 0, s[0:1]
	s_mov_b64 s[0:1], 0x5800
	v_lshl_add_u64 v[20:21], v[2:3], 0, s[0:1]
	s_mov_b64 s[0:1], 0x5c00
	v_lshl_add_u64 v[22:23], v[2:3], 0, s[0:1]
	v_lshlrev_b64 v[2:3], 13, v[12:13]
	v_lshl_or_b32 v2, v4, 4, v2
	v_lshl_add_u64 v[0:1], s[28:29], 0, v[2:3]
	s_mov_b64 s[0:1], 0x1000
	v_lshl_add_u64 v[24:25], v[0:1], 0, s[0:1]
	v_lshlrev_b64 v[0:1], 12, v[12:13]
	v_lshl_or_b32 v0, v4, 3, v0
	v_lshl_add_u64 v[0:1], s[30:31], 0, v[0:1]
	s_mov_b64 s[0:1], 0x15550800
	v_lshl_add_u64 v[26:27], v[0:1], 0, s[0:1]
	v_mov_b32_e32 v13, 0x358637bd
	s_mov_b32 s0, 0xf800000
	s_movk_i32 s1, 0x7fff
	global_load_dwordx4 v[100:103], v[14:15], off
	global_load_dwordx4 v[104:107], v[14:15], off offset:1024
	global_load_dwordx4 v[108:111], v[14:15], off offset:2048
	global_load_dwordx4 v[112:115], v[14:15], off offset:3072
	global_load_dwordx4 v[116:119], v[16:17], off
	global_load_dwordx4 v[120:123], v[18:19], off
	global_load_dwordx4 v[124:127], v[20:21], off
	global_load_dwordx4 v[128:131], v[22:23], off
	global_load_dwordx4 v[196:199], v[24:25], off offset:-4096
	global_load_dwordx4 v[200:203], v[24:25], off offset:-3072
	global_load_dwordx4 v[204:207], v[24:25], off offset:-2048
	global_load_dwordx4 v[208:211], v[24:25], off offset:-1024
	global_load_dwordx4 v[212:215], v[24:25], off
	global_load_dwordx4 v[216:219], v[24:25], off offset:1024
	global_load_dwordx4 v[220:223], v[24:25], off offset:2048
	global_load_dwordx4 v[224:227], v[24:25], off offset:3072
	v_add_u32_e32 v12, s42, v12
	v_lshl_add_u64 v[24:25], v[24:25], 0, s[12:13]
	v_cmp_lt_i32_e32 vcc, s1, v12
	s_mov_b64 s[88:89], vcc
	s_mov_b64 s[86:87], exec
	s_andn2_b64 exec, exec, s[88:89]
	global_load_dwordx4 v[164:167], v[24:25], off offset:-4096
	global_load_dwordx4 v[168:171], v[24:25], off offset:-3072
	global_load_dwordx4 v[172:175], v[24:25], off offset:-2048
	global_load_dwordx4 v[176:179], v[24:25], off offset:-1024
	global_load_dwordx4 v[180:183], v[24:25], off
	global_load_dwordx4 v[184:187], v[24:25], off offset:1024
	global_load_dwordx4 v[188:191], v[24:25], off offset:2048
	global_load_dwordx4 v[228:231], v[24:25], off offset:3072
	s_mov_b64 exec, s[86:87]
	v_add_u32_e32 v12, s42, v12
	v_lshl_add_u64 v[24:25], v[24:25], 0, s[12:13]
	s_waitcnt vmcnt(0)
.LBB0_2226:
	s_waitcnt vmcnt(16)
	v_mov_b32_e32 v36, v196
	v_mov_b32_e32 v37, v197
	v_mov_b32_e32 v38, v198
	v_mov_b32_e32 v39, v199
	v_mov_b32_e32 v40, v200
	v_mov_b32_e32 v41, v201
	v_mov_b32_e32 v42, v202
	v_mov_b32_e32 v43, v203
	v_mov_b32_e32 v44, v204
	v_mov_b32_e32 v45, v205
	v_mov_b32_e32 v46, v206
	v_mov_b32_e32 v47, v207
	v_mov_b32_e32 v48, v208
	v_mov_b32_e32 v49, v209
	v_mov_b32_e32 v50, v210
	v_mov_b32_e32 v51, v211
	v_mov_b32_e32 v52, v212
	v_mov_b32_e32 v53, v213
	v_mov_b32_e32 v54, v214
	v_mov_b32_e32 v55, v215
	v_mov_b32_e32 v8, v216
	v_mov_b32_e32 v9, v217
	v_mov_b32_e32 v10, v218
	v_mov_b32_e32 v11, v219
	v_mov_b32_e32 v4, v220
	v_mov_b32_e32 v5, v221
	v_mov_b32_e32 v6, v222
	v_mov_b32_e32 v7, v223
	v_mov_b32_e32 v0, v224
	v_mov_b32_e32 v1, v225
	v_mov_b32_e32 v2, v226
	v_mov_b32_e32 v3, v227
	s_or_b64 s[16:17], s[88:89], s[16:17]
	v_cmp_lt_i32_e32 vcc, s1, v12
	s_or_b64 s[88:89], vcc, s[88:89]
	s_mov_b64 s[86:87], exec
	s_andn2_b64 exec, exec, s[88:89]
	global_load_dwordx4 v[196:199], v[24:25], off offset:-4096
	global_load_dwordx4 v[200:203], v[24:25], off offset:-3072
	global_load_dwordx4 v[204:207], v[24:25], off offset:-2048
	global_load_dwordx4 v[208:211], v[24:25], off offset:-1024
	global_load_dwordx4 v[212:215], v[24:25], off
	global_load_dwordx4 v[216:219], v[24:25], off offset:1024
	global_load_dwordx4 v[220:223], v[24:25], off offset:2048
	global_load_dwordx4 v[224:227], v[24:25], off offset:3072
	s_mov_b64 exec, s[86:87]
	v_add_u32_e32 v12, s42, v12
	v_lshl_add_u64 v[24:25], v[24:25], 0, s[12:13]
	v_mul_f32_e32 v35, v37, v37
	v_mul_f32_e32 v68, v41, v41
	v_mul_f32_e32 v69, v45, v45
	v_fmac_f32_e32 v35, v36, v36
	v_fmac_f32_e32 v68, v40, v40
	v_mul_f32_e32 v70, v49, v49
	v_fmac_f32_e32 v69, v44, v44
	v_fmac_f32_e32 v35, v38, v38
	v_fmac_f32_e32 v68, v42, v42
	v_mul_f32_e32 v71, v53, v53
	v_fmac_f32_e32 v70, v48, v48
	v_fmac_f32_e32 v69, v46, v46
	v_fmac_f32_e32 v35, v39, v39
	v_fmac_f32_e32 v68, v43, v43
	v_mul_f32_e32 v72, v9, v9
	v_mov_b32_e32 v62, v5
	v_mov_b32_e32 v63, v1
	v_fmac_f32_e32 v71, v52, v52
	v_fmac_f32_e32 v70, v50, v50
	v_fmac_f32_e32 v69, v47, v47
	v_add_f32_e32 v35, v35, v68
	v_mov_b32_e32 v60, v4
	v_mov_b32_e32 v61, v0
	v_fmac_f32_e32 v72, v8, v8
	v_pk_mul_f32 v[62:63], v[62:63], v[62:63]
	v_fmac_f32_e32 v71, v54, v54
	v_fmac_f32_e32 v70, v51, v51
	v_add_f32_e32 v35, v35, v69
	v_mov_b32_e32 v64, v6
	v_mov_b32_e32 v65, v2
	v_fmac_f32_e32 v72, v10, v10
	v_pk_fma_f32 v[60:61], v[60:61], v[60:61], v[62:63]
	v_fmac_f32_e32 v71, v55, v55
	v_add_f32_e32 v35, v35, v70
	v_mov_b32_e32 v66, v7
	v_mov_b32_e32 v67, v3
	v_fmac_f32_e32 v72, v11, v11
	v_pk_fma_f32 v[60:61], v[64:65], v[64:65], v[60:61]
	v_add_f32_e32 v35, v35, v71
	v_pk_fma_f32 v[60:61], v[66:67], v[66:67], v[60:61]
	v_add_f32_e32 v35, v35, v72
	v_add_f32_e32 v35, v35, v60
	v_add_f32_e32 v35, v35, v61
	ds_bpermute_b32 v60, v28, v35
	s_waitcnt lgkmcnt(0)
; __device__ __forceinline__ void st_bf4(bf16_t* p, const f32x4 v) { u32x2 w; w.x = cvt_pk_bf16(v[0], v[1]); w.y = cvt_pk_bf16(v[2], v[3]); *(u32x2*)p = w; }
; __device__ __forceinline__ float wave_sum(float v) {
; #pragma unroll
;     for (int o = 32; o >= 1; o >>= 1) v += __shfl_xor(v, o);
;     return v;
; }
; template <bool F32OUT>
; __device__ __forceinline__ void rmsnorm_rows(const float* x, const float* w, bf16_t* outb, float* outf) {
;     ...
;     for (int row = gw; row < T_; row += nw) {
;         const float* xr = x + (size_t)row * D_; f32x4 v[8]; float ss = 0.f;
; #pragma unroll
;         for (int i = 0; i < 8; ++i) { v[i] = *(const f32x4*)(xr + i * 256 + lane * 4); ss += v[i][0] * v[i][0] + v[i][1] * v[i][1] + v[i][2] * v[i][2] + v[i][3] * v[i][3]; }
;         ss = wave_sum(ss);
;         const float rstd = 1.0f / sqrtf(ss * (1.0f / D_) + 1e-6f);
; #pragma unroll
;         for (int i = 0; i < 8; ++i) { const f32x4 wv = *(const f32x4*)(w + i * 256 + lane * 4); const f32x4 y = v[i] * rstd * wv;
;             if (F32OUT) *(f32x4*)(outf + (size_t)row * D_ + i * 256 + lane * 4) = y; else st_bf4(outb + (size_t)row * D_ + i * 256 + lane * 4, y); }
;     }
	v_add_f32_e32 v35, v35, v60
	ds_bpermute_b32 v60, v29, v35
	s_waitcnt lgkmcnt(0)
	v_add_f32_e32 v35, v35, v60
	ds_bpermute_b32 v60, v30, v35
	s_waitcnt lgkmcnt(0)
	v_add_f32_e32 v35, v35, v60
	ds_bpermute_b32 v60, v31, v35
	s_waitcnt lgkmcnt(0)
	v_add_f32_e32 v35, v35, v60
	ds_bpermute_b32 v60, v32, v35
	s_waitcnt lgkmcnt(0)
	v_add_f32_e32 v35, v35, v60
	ds_bpermute_b32 v60, v33, v35
	s_waitcnt lgkmcnt(0)
	v_add_f32_e32 v35, v35, v60
	v_fmamk_f32 v35, v35, 0x3a000000, v13
	v_mul_f32_e32 v60, 0x4f800000, v35
	v_cmp_gt_f32_e32 vcc, s0, v35
	s_nop 1
	v_cndmask_b32_e32 v35, v35, v60, vcc
	v_sqrt_f32_e32 v60, v35
	s_nop 0
	v_add_u32_e32 v61, -1, v60
	v_add_u32_e32 v62, 1, v60
	v_fma_f32 v63, -v61, v60, v35
	v_fma_f32 v64, -v62, v60, v35
	v_cmp_ge_f32_e64 s[8:9], 0, v63
	s_nop 1
	v_cndmask_b32_e64 v60, v60, v61, s[8:9]
	v_cmp_lt_f32_e64 s[8:9], 0, v64
	s_nop 1
	v_cndmask_b32_e64 v60, v60, v62, s[8:9]
	v_mul_f32_e32 v61, 0x37800000, v60
	v_cndmask_b32_e32 v60, v60, v61, vcc
	v_cmp_class_f32_e32 vcc, v35, v34
	s_nop 1
	v_cndmask_b32_e32 v35, v60, v35, vcc
	v_div_scale_f32 v60, s[8:9], v35, v35, 1.0
	v_rcp_f32_e32 v62, v60
	v_div_scale_f32 v61, vcc, 1.0, v35, 1.0
	v_fma_f32 v63, -v60, v62, 1.0
	v_fmac_f32_e32 v62, v63, v62
	v_mul_f32_e32 v63, v61, v62
	v_fma_f32 v64, -v60, v63, v61
	v_fmac_f32_e32 v63, v64, v62
	v_fma_f32 v60, -v60, v63, v61
	v_div_fmas_f32 v60, v60, v62, v63
	v_div_fixup_f32 v60, v60, v35, 1.0
	v_pk_mul_f32 v[36:37], v[36:37], v[60:61] op_sel_hi:[1,0]
	v_pk_mul_f32 v[38:39], v[38:39], v[60:61] op_sel_hi:[1,0]
	v_pk_mul_f32 v[36:37], v[100:101], v[36:37]
	v_pk_mul_f32 v[38:39], v[102:103], v[38:39]
	v_cvt_pk_bf16_f32 v36, v36, v37
	s_nop 0
	v_cvt_pk_bf16_f32 v37, v38, v39
	global_store_dwordx2 v[26:27], v[36:37], off
	v_pk_mul_f32 v[40:41], v[40:41], v[60:61] op_sel_hi:[1,0]
	v_pk_mul_f32 v[42:43], v[42:43], v[60:61] op_sel_hi:[1,0]
	v_pk_mul_f32 v[40:41], v[104:105], v[40:41]
	v_pk_mul_f32 v[42:43], v[106:107], v[42:43]
	v_cvt_pk_bf16_f32 v40, v40, v41
	s_nop 0
	v_cvt_pk_bf16_f32 v41, v42, v43
	global_store_dwordx2 v[26:27], v[40:41], off offset:512
	v_pk_mul_f32 v[44:45], v[44:45], v[60:61] op_sel_hi:[1,0]
	v_pk_mul_f32 v[46:47], v[46:47], v[60:61] op_sel_hi:[1,0]
	v_pk_mul_f32 v[44:45], v[108:109], v[44:45]
	v_pk_mul_f32 v[46:47], v[110:111], v[46:47]
	v_cvt_pk_bf16_f32 v44, v44, v45
	s_nop 0
	v_cvt_pk_bf16_f32 v45, v46, v47
	global_store_dwordx2 v[26:27], v[44:45], off offset:1024
	v_pk_mul_f32 v[48:49], v[48:49], v[60:61] op_sel_hi:[1,0]
	v_pk_mul_f32 v[50:51], v[50:51], v[60:61] op_sel_hi:[1,0]
	v_pk_mul_f32 v[48:49], v[112:113], v[48:49]
	v_pk_mul_f32 v[50:51], v[114:115], v[50:51]
	v_cvt_pk_bf16_f32 v48, v48, v49
	s_nop 0
	v_cvt_pk_bf16_f32 v49, v50, v51
	global_store_dwordx2 v[26:27], v[48:49], off offset:1536
	v_pk_mul_f32 v[52:53], v[52:53], v[60:61] op_sel_hi:[1,0]
	v_pk_mul_f32 v[54:55], v[54:55], v[60:61] op_sel_hi:[1,0]
	v_pk_mul_f32 v[52:53], v[116:117], v[52:53]
	v_pk_mul_f32 v[54:55], v[118:119], v[54:55]
	v_cvt_pk_bf16_f32 v52, v52, v53
	s_nop 0
	v_cvt_pk_bf16_f32 v53, v54, v55
	global_store_dwordx2 v[26:27], v[52:53], off offset:2048
	v_pk_mul_f32 v[8:9], v[8:9], v[60:61] op_sel_hi:[1,0]
	v_pk_mul_f32 v[10:11], v[10:11], v[60:61] op_sel_hi:[1,0]
	v_pk_mul_f32 v[8:9], v[120:121], v[8:9]
	v_pk_mul_f32 v[10:11], v[122:123], v[10:11]
	v_cvt_pk_bf16_f32 v8, v8, v9
	s_nop 0
	v_cvt_pk_bf16_f32 v9, v10, v11
	global_store_dwordx2 v[26:27], v[8:9], off offset:2560
	v_pk_mul_f32 v[4:5], v[4:5], v[60:61] op_sel_hi:[1,0]
	v_pk_mul_f32 v[6:7], v[6:7], v[60:61] op_sel_hi:[1,0]
	v_pk_mul_f32 v[4:5], v[124:125], v[4:5]
	v_pk_mul_f32 v[6:7], v[126:127], v[6:7]
	v_cvt_pk_bf16_f32 v4, v4, v5
	s_nop 0
	v_cvt_pk_bf16_f32 v5, v6, v7
	global_store_dwordx2 v[26:27], v[4:5], off offset:3072
	v_pk_mul_f32 v[0:1], v[0:1], v[60:61] op_sel_hi:[1,0]
	v_pk_mul_f32 v[2:3], v[2:3], v[60:61] op_sel_hi:[1,0]
	v_pk_mul_f32 v[0:1], v[128:129], v[0:1]
	v_pk_mul_f32 v[2:3], v[130:131], v[2:3]
	v_cvt_pk_bf16_f32 v0, v0, v1
	s_nop 0
	v_cvt_pk_bf16_f32 v1, v2, v3
	global_store_dwordx2 v[26:27], v[0:1], off offset:3584
	v_lshl_add_u64 v[26:27], v[26:27], 0, s[14:15]
	s_andn2_b64 exec, exec, s[16:17]
	s_cbranch_execz .Lmy_rms3x_3
	s_waitcnt vmcnt(16)
	v_mov_b32_e32 v36, v164
	v_mov_b32_e32 v37, v165
	v_mov_b32_e32 v38, v166
	v_mov_b32_e32 v39, v167
	v_mov_b32_e32 v40, v168
	v_mov_b32_e32 v41, v169
	v_mov_b32_e32 v42, v170
	v_mov_b32_e32 v43, v171
	v_mov_b32_e32 v44, v172
	v_mov_b32_e32 v45, v173
	v_mov_b32_e32 v46, v174
	v_mov_b32_e32 v47, v175
	v_mov_b32_e32 v48, v176
	v_mov_b32_e32 v49, v177
	v_mov_b32_e32 v50, v178
	v_mov_b32_e32 v51, v179
	v_mov_b32_e32 v52, v180
	v_mov_b32_e32 v53, v181
	v_mov_b32_e32 v54, v182
	v_mov_b32_e32 v55, v183
	v_mov_b32_e32 v8, v184
	v_mov_b32_e32 v9, v185
	v_mov_b32_e32 v10, v186
	v_mov_b32_e32 v11, v187
	v_mov_b32_e32 v4, v188
	v_mov_b32_e32 v5, v189
	v_mov_b32_e32 v6, v190
	v_mov_b32_e32 v7, v191
	v_mov_b32_e32 v0, v228
	v_mov_b32_e32 v1, v229
	v_mov_b32_e32 v2, v230
	v_mov_b32_e32 v3, v231
	s_or_b64 s[16:17], s[88:89], s[16:17]
	v_cmp_lt_i32_e32 vcc, s1, v12
	s_or_b64 s[88:89], vcc, s[88:89]
	s_mov_b64 s[86:87], exec
	s_andn2_b64 exec, exec, s[88:89]
	global_load_dwordx4 v[164:167], v[24:25], off offset:-4096
	global_load_dwordx4 v[168:171], v[24:25], off offset:-3072
	global_load_dwordx4 v[172:175], v[24:25], off offset:-2048
	global_load_dwordx4 v[176:179], v[24:25], off offset:-1024
	global_load_dwordx4 v[180:183], v[24:25], off
	global_load_dwordx4 v[184:187], v[24:25], off offset:1024
	global_load_dwordx4 v[188:191], v[24:25], off offset:2048
	global_load_dwordx4 v[228:231], v[24:25], off offset:3072
; __device__ __forceinline__ void st_bf4(bf16_t* p, const f32x4 v) { u32x2 w; w.x = cvt_pk_bf16(v[0], v[1]); w.y = cvt_pk_bf16(v[2], v[3]); *(u32x2*)p = w; }
; __device__ __forceinline__ float wave_sum(float v) {
; #pragma unroll
;     for (int o = 32; o >= 1; o >>= 1) v += __shfl_xor(v, o);
;     return v;
; }
; template <bool F32OUT>
; __device__ __forceinline__ void rmsnorm_rows(const float* x, const float* w, bf16_t* outb, float* outf) {
;     ...
;     for (int row = gw; row < T_; row += nw) {
;         const float* xr = x + (size_t)row * D_; f32x4 v[8]; float ss = 0.f;
; #pragma unroll
;         for (int i = 0; i < 8; ++i) { v[i] = *(const f32x4*)(xr + i * 256 + lane * 4); ss += v[i][0] * v[i][0] + v[i][1] * v[i][1] + v[i][2] * v[i][2] + v[i][3] * v[i][3]; }
;         ss = wave_sum(ss);
;         const float rstd = 1.0f / sqrtf(ss * (1.0f / D_) + 1e-6f);
; #pragma unroll
;         for (int i = 0; i < 8; ++i) { const f32x4 wv = *(const f32x4*)(w + i * 256 + lane * 4); const f32x4 y = v[i] * rstd * wv;
;             if (F32OUT) *(f32x4*)(outf + (size_t)row * D_ + i * 256 + lane * 4) = y; else st_bf4(outb + (size_t)row * D_ + i * 256 + lane * 4, y); }
;     }
	s_mov_b64 exec, s[86:87]
	v_add_u32_e32 v12, s42, v12
	v_lshl_add_u64 v[24:25], v[24:25], 0, s[12:13]
	v_mul_f32_e32 v35, v37, v37
	v_mul_f32_e32 v68, v41, v41
	v_mul_f32_e32 v69, v45, v45
	v_fmac_f32_e32 v35, v36, v36
	v_fmac_f32_e32 v68, v40, v40
	v_mul_f32_e32 v70, v49, v49
	v_fmac_f32_e32 v69, v44, v44
	v_fmac_f32_e32 v35, v38, v38
	v_fmac_f32_e32 v68, v42, v42
	v_mul_f32_e32 v71, v53, v53
	v_fmac_f32_e32 v70, v48, v48
	v_fmac_f32_e32 v69, v46, v46
	v_fmac_f32_e32 v35, v39, v39
	v_fmac_f32_e32 v68, v43, v43
	v_mul_f32_e32 v72, v9, v9
	v_mov_b32_e32 v62, v5
	v_mov_b32_e32 v63, v1
	v_fmac_f32_e32 v71, v52, v52
	v_fmac_f32_e32 v70, v50, v50
	v_fmac_f32_e32 v69, v47, v47
	v_add_f32_e32 v35, v35, v68
	v_mov_b32_e32 v60, v4
	v_mov_b32_e32 v61, v0
	v_fmac_f32_e32 v72, v8, v8
	v_pk_mul_f32 v[62:63], v[62:63], v[62:63]
	v_fmac_f32_e32 v71, v54, v54
	v_fmac_f32_e32 v70, v51, v51
	v_add_f32_e32 v35, v35, v69
	v_mov_b32_e32 v64, v6
	v_mov_b32_e32 v65, v2
	v_fmac_f32_e32 v72, v10, v10
	v_pk_fma_f32 v[60:61], v[60:61], v[60:61], v[62:63]
	v_fmac_f32_e32 v71, v55, v55
	v_add_f32_e32 v35, v35, v70
	v_mov_b32_e32 v66, v7
	v_mov_b32_e32 v67, v3
	v_fmac_f32_e32 v72, v11, v11
	v_pk_fma_f32 v[60:61], v[64:65], v[64:65], v[60:61]
	v_add_f32_e32 v35, v35, v71
	v_pk_fma_f32 v[60:61], v[66:67], v[66:67], v[60:61]
	v_add_f32_e32 v35, v35, v72
	v_add_f32_e32 v35, v35, v60
	v_add_f32_e32 v35, v35, v61
	ds_bpermute_b32 v60, v28, v35
	s_waitcnt lgkmcnt(0)
	v_add_f32_e32 v35, v35, v60
	ds_bpermute_b32 v60, v29, v35
	s_waitcnt lgkmcnt(0)
	v_add_f32_e32 v35, v35, v60
	ds_bpermute_b32 v60, v30, v35
	s_waitcnt lgkmcnt(0)
	v_add_f32_e32 v35, v35, v60
	ds_bpermute_b32 v60, v31, v35
	s_waitcnt lgkmcnt(0)
	v_add_f32_e32 v35, v35, v60
	ds_bpermute_b32 v60, v32, v35
	s_waitcnt lgkmcnt(0)
	v_add_f32_e32 v35, v35, v60
	ds_bpermute_b32 v60, v33, v35
	s_waitcnt lgkmcnt(0)
	v_add_f32_e32 v35, v35, v60
	v_fmamk_f32 v35, v35, 0x3a000000, v13
	v_mul_f32_e32 v60, 0x4f800000, v35
	v_cmp_gt_f32_e32 vcc, s0, v35
	s_nop 1
	v_cndmask_b32_e32 v35, v35, v60, vcc
	v_sqrt_f32_e32 v60, v35
	s_nop 0
	v_add_u32_e32 v61, -1, v60
	v_add_u32_e32 v62, 1, v60
	v_fma_f32 v63, -v61, v60, v35
	v_fma_f32 v64, -v62, v60, v35
	v_cmp_ge_f32_e64 s[8:9], 0, v63
	s_nop 1
	v_cndmask_b32_e64 v60, v60, v61, s[8:9]
	v_cmp_lt_f32_e64 s[8:9], 0, v64
	s_nop 1
	v_cndmask_b32_e64 v60, v60, v62, s[8:9]
	v_mul_f32_e32 v61, 0x37800000, v60
	v_cndmask_b32_e32 v60, v60, v61, vcc
	v_cmp_class_f32_e32 vcc, v35, v34
	s_nop 1
	v_cndmask_b32_e32 v35, v60, v35, vcc
	v_div_scale_f32 v60, s[8:9], v35, v35, 1.0
	v_rcp_f32_e32 v62, v60
	v_div_scale_f32 v61, vcc, 1.0, v35, 1.0
	v_fma_f32 v63, -v60, v62, 1.0
	v_fmac_f32_e32 v62, v63, v62
	v_mul_f32_e32 v63, v61, v62
	v_fma_f32 v64, -v60, v63, v61
	v_fmac_f32_e32 v63, v64, v62
	v_fma_f32 v60, -v60, v63, v61
	v_div_fmas_f32 v60, v60, v62, v63
	v_div_fixup_f32 v60, v60, v35, 1.0
	v_pk_mul_f32 v[36:37], v[36:37], v[60:61] op_sel_hi:[1,0]
	v_pk_mul_f32 v[38:39], v[38:39], v[60:61] op_sel_hi:[1,0]
	v_pk_mul_f32 v[36:37], v[100:101], v[36:37]
	v_pk_mul_f32 v[38:39], v[102:103], v[38:39]
	v_cvt_pk_bf16_f32 v36, v36, v37
	s_nop 0
	v_cvt_pk_bf16_f32 v37, v38, v39
	global_store_dwordx2 v[26:27], v[36:37], off
	v_pk_mul_f32 v[40:41], v[40:41], v[60:61] op_sel_hi:[1,0]
	v_pk_mul_f32 v[42:43], v[42:43], v[60:61] op_sel_hi:[1,0]
	v_pk_mul_f32 v[40:41], v[104:105], v[40:41]
	v_pk_mul_f32 v[42:43], v[106:107], v[42:43]
	v_cvt_pk_bf16_f32 v40, v40, v41
	s_nop 0
	v_cvt_pk_bf16_f32 v41, v42, v43
	global_store_dwordx2 v[26:27], v[40:41], off offset:512
	v_pk_mul_f32 v[44:45], v[44:45], v[60:61] op_sel_hi:[1,0]
	v_pk_mul_f32 v[46:47], v[46:47], v[60:61] op_sel_hi:[1,0]
	v_pk_mul_f32 v[44:45], v[108:109], v[44:45]
	v_pk_mul_f32 v[46:47], v[110:111], v[46:47]
	v_cvt_pk_bf16_f32 v44, v44, v45
	s_nop 0
	v_cvt_pk_bf16_f32 v45, v46, v47
	global_store_dwordx2 v[26:27], v[44:45], off offset:1024
	v_pk_mul_f32 v[48:49], v[48:49], v[60:61] op_sel_hi:[1,0]
	v_pk_mul_f32 v[50:51], v[50:51], v[60:61] op_sel_hi:[1,0]
	v_pk_mul_f32 v[48:49], v[112:113], v[48:49]
	v_pk_mul_f32 v[50:51], v[114:115], v[50:51]
	v_cvt_pk_bf16_f32 v48, v48, v49
	s_nop 0
	v_cvt_pk_bf16_f32 v49, v50, v51
	global_store_dwordx2 v[26:27], v[48:49], off offset:1536
	v_pk_mul_f32 v[52:53], v[52:53], v[60:61] op_sel_hi:[1,0]
	v_pk_mul_f32 v[54:55], v[54:55], v[60:61] op_sel_hi:[1,0]
	v_pk_mul_f32 v[52:53], v[116:117], v[52:53]
	v_pk_mul_f32 v[54:55], v[118:119], v[54:55]
	v_cvt_pk_bf16_f32 v52, v52, v53
	s_nop 0
	v_cvt_pk_bf16_f32 v53, v54, v55
	global_store_dwordx2 v[26:27], v[52:53], off offset:2048
	v_pk_mul_f32 v[8:9], v[8:9], v[60:61] op_sel_hi:[1,0]
	v_pk_mul_f32 v[10:11], v[10:11], v[60:61] op_sel_hi:[1,0]
	v_pk_mul_f32 v[8:9], v[120:121], v[8:9]
	v_pk_mul_f32 v[10:11], v[122:123], v[10:11]
	v_cvt_pk_bf16_f32 v8, v8, v9
	s_nop 0
	v_cvt_pk_bf16_f32 v9, v10, v11
	global_store_dwordx2 v[26:27], v[8:9], off offset:2560
	v_pk_mul_f32 v[4:5], v[4:5], v[60:61] op_sel_hi:[1,0]
	v_pk_mul_f32 v[6:7], v[6:7], v[60:61] op_sel_hi:[1,0]
	v_pk_mul_f32 v[4:5], v[124:125], v[4:5]
	v_pk_mul_f32 v[6:7], v[126:127], v[6:7]
	v_cvt_pk_bf16_f32 v4, v4, v5
	s_nop 0
	v_cvt_pk_bf16_f32 v5, v6, v7
	global_store_dwordx2 v[26:27], v[4:5], off offset:3072
	v_pk_mul_f32 v[0:1], v[0:1], v[60:61] op_sel_hi:[1,0]
	v_pk_mul_f32 v[2:3], v[2:3], v[60:61] op_sel_hi:[1,0]
	v_pk_mul_f32 v[0:1], v[128:129], v[0:1]
	v_pk_mul_f32 v[2:3], v[130:131], v[2:3]
	v_cvt_pk_bf16_f32 v0, v0, v1
	s_nop 0
	v_cvt_pk_bf16_f32 v1, v2, v3
	global_store_dwordx2 v[26:27], v[0:1], off offset:3584
	v_lshl_add_u64 v[26:27], v[26:27], 0, s[14:15]
	s_andn2_b64 exec, exec, s[16:17]
	s_cbranch_execnz .LBB0_2226
; __device__ __forceinline__ unsigned xb_ld(unsigned* p)              { return __hip_atomic_load(p, __ATOMIC_RELAXED, __HIP_MEMORY_SCOPE_AGENT); }
; __device__ __forceinline__ unsigned xb_add(unsigned* p, unsigned v) { return __hip_atomic_fetch_add(p, v, __ATOMIC_RELAXED, __HIP_MEMORY_SCOPE_AGENT); }
; __device__ __forceinline__ void xcd_barrier_complete(unsigned* bar, unsigned x, unsigned& nloc, unsigned& nx) {
;     const unsigned G = gridDim.x * gridDim.y * gridDim.z;
;     unsigned sum, cnt, mine, sp = 0u;
;     for (;;) {
;         sum = 0u; cnt = 0u; mine = 0u;
; #pragma unroll
;         for (unsigned j = 0; j < 16; ++j) { const unsigned c = xb_ld(&bar[XB_XCNT(j)]); sum += c; cnt += (c > 0u) ? 1u : 0u; mine = (j == x) ? c : mine; }
; __device__ __forceinline__ void xcd_barrier(const XcdBarrier& b) {
;     asm volatile("s_waitcnt vmcnt(0)" ::: "memory");
;     __syncthreads();
;     if (threadIdx.x == 0) {
;         unsigned* bar = b.bar;
;         __builtin_amdgcn_s_waitcnt(0);
;         unsigned nloc = b.st[0], nx = b.st[1];
;         if (nloc == 0u) { xcd_barrier_complete(bar, b.x, nloc, nx); b.st[0] = nloc; b.st[1] = nx; }
;         const unsigned old = xb_add(&bar[XB_XSUB(b.x)], 1u);
.Lmy_rms3x_3:
.LBB0_2227:
	s_or_b64 exec, exec, s[10:11]
	s_waitcnt vmcnt(0)
	s_barrier
	s_mov_b64 s[8:9], exec
	v_readlane_b32 s0, v248, 20
	v_readlane_b32 s1, v248, 21
	s_and_b64 s[0:1], s[8:9], s[0:1]
	s_mov_b64 exec, s[0:1]
	s_cbranch_execz .LBB0_2279
	s_add_i32 s0, 0, 0x22000
	v_mov_b32_e32 v0, s0
	s_waitcnt vmcnt(0) expcnt(0) lgkmcnt(0)
	ds_read_b32 v2, v0
	s_add_i32 s0, 0, 0x22004
	v_mov_b32_e32 v0, s0
	ds_read_b32 v0, v0
	s_waitcnt lgkmcnt(1)
	v_cmp_ne_u32_e32 vcc, 0, v2
	s_cbranch_vccnz .LBB0_2243
	v_readlane_b32 s0, v248, 0
	v_readlane_b32 s1, v248, 1
	s_load_dword s1, s[0:1], 0x14
	s_mov_b32 s0, 1
	v_mov_b32_e32 v16, 0
	s_waitcnt lgkmcnt(0)
	s_lshr_b32 s12, s1, 16
	s_and_b32 s1, s1, 0xffff
	s_cmp_lg_u32 s1, 0
	s_cselect_b64 s[10:11], -1, 0
	s_cmp_lg_u64 s[10:11], 0
	s_addc_u32 s1, s69, 0
	s_cmp_lg_u32 s12, 0
	s_cselect_b64 s[10:11], -1, 0
	s_cmp_lg_u64 s[10:11], 0
	s_mul_i32 s1, s1, s68
	s_addc_u32 s10, s94, 0
	s_mul_i32 s1, s1, s10
	s_add_u32 s10, s30, 0x3e150a00
	s_addc_u32 s11, s31, 0
	s_add_u32 s12, s30, 0x3e150c00
	s_addc_u32 s13, s31, 0
	s_add_u32 s14, s30, 0x3e150d00
	s_addc_u32 s15, s31, 0
	s_add_u32 s16, s30, 0x3e150e00
	s_addc_u32 s17, s31, 0
	s_add_u32 s18, s30, 0x3e150f00
	s_addc_u32 s19, s31, 0
	s_add_u32 s20, s30, 0x3e151000
	s_addc_u32 s21, s31, 0
	s_add_u32 s22, s30, 0x3e151100
	s_addc_u32 s23, s31, 0
	s_add_u32 s24, s30, 0x3e151200
	s_addc_u32 s25, s31, 0
	s_add_u32 s36, s30, 0x3e151300
	s_addc_u32 s37, s31, 0
	s_add_u32 s38, s30, 0x3e151400
	s_addc_u32 s39, s31, 0
	s_add_u32 s54, s30, 0x3e151500
	s_addc_u32 s55, s31, 0
	s_add_u32 s56, s30, 0x3e151600
	s_addc_u32 s57, s31, 0
	s_add_u32 s58, s30, 0x3e151700
	s_addc_u32 s59, s31, 0
	s_add_u32 s64, s30, 0x3e151800
	s_addc_u32 s65, s31, 0
	s_add_u32 s66, s30, 0x3e151900
	s_addc_u32 s67, s31, 0
	s_add_u32 s78, s30, 0x3e151a00
	s_addc_u32 s79, s31, 0
	s_add_u32 s80, s30, 0x3e151b00
	s_addc_u32 s81, s31, 0
	s_branch .LBB0_2231

; __device__ __forceinline__ int opaque_tid() { int t = threadIdx.x; asm volatile("" : "+v"(t)); return t; }
; template <bool F32OUT>
; __device__ __forceinline__ void rmsnorm_rows(const float* x, const float* w, bf16_t* outb, float* outf) {
;     const int tid_ = opaque_tid(); const int lane = tid_ & 63, gw = blockIdx.x * 8 + (tid_ >> 6), nw = gridDim.x * 8;
;     for (int row = gw; row < T_; row += nw) {
;         const float* xr = x + (size_t)row * D_; f32x4 v[8]; float ss = 0.f;
; #pragma unroll
;         for (int i = 0; i < 8; ++i) { v[i] = *(const f32x4*)(xr + i * 256 + lane * 4); ss += v[i][0] * v[i][0] + v[i][1] * v[i][1] + v[i][2] * v[i][2] + v[i][3] * v[i][3]; }
.LBB0_2423:
	s_or_b64 exec, exec, s[8:9]
	s_waitcnt lgkmcnt(0)
	v_mov_b32_e32 v0, v192
	s_barrier
	s_mov_b32 s0, 0x8000
	v_ashrrev_i32_e32 v1, 6, v0
	v_add_u32_e32 v12, s92, v1
	v_cmp_gt_i32_e32 vcc, s0, v12
	s_and_saveexec_b64 s[10:11], vcc
	s_cbranch_execz .LBB0_2426
	v_mbcnt_hi_u32_b32 v1, -1, v193
	v_and_b32_e32 v2, 64, v1
	v_add_u32_e32 v2, 64, v2
	v_xor_b32_e32 v3, 32, v1
	v_cmp_lt_i32_e32 vcc, v3, v2
	s_mov_b64 s[0:1], 0x2000
	v_ashrrev_i32_e32 v13, 31, v12
	v_cndmask_b32_e32 v3, v1, v3, vcc
	v_lshlrev_b32_e32 v28, 2, v3
	v_xor_b32_e32 v3, 16, v1
	v_cmp_lt_i32_e32 vcc, v3, v2
	v_and_b32_e32 v4, 63, v0
	s_ashr_i32 s43, s42, 31
	v_cndmask_b32_e32 v3, v1, v3, vcc
	v_lshlrev_b32_e32 v29, 2, v3
	v_xor_b32_e32 v3, 8, v1
	v_cmp_lt_i32_e32 vcc, v3, v2
	s_lshl_b64 s[12:13], s[42:43], 13
	s_lshl_b64 s[14:15], s[42:43], 12
	v_cndmask_b32_e32 v3, v1, v3, vcc
	v_lshlrev_b32_e32 v30, 2, v3
	v_xor_b32_e32 v3, 4, v1
	v_cmp_lt_i32_e32 vcc, v3, v2
	s_mov_b64 s[16:17], 0
	v_mov_b32_e32 v34, 0x260
	v_cndmask_b32_e32 v3, v1, v3, vcc
	v_lshlrev_b32_e32 v31, 2, v3
	v_xor_b32_e32 v3, 2, v1
	v_cmp_lt_i32_e32 vcc, v3, v2
	s_nop 1
	v_cndmask_b32_e32 v3, v1, v3, vcc
	v_lshlrev_b32_e32 v32, 2, v3
	v_xor_b32_e32 v3, 1, v1
	v_cmp_lt_i32_e32 vcc, v3, v2
	s_nop 1
	v_cndmask_b32_e32 v1, v1, v3, vcc
	v_lshlrev_b32_e32 v33, 2, v1
	v_lshlrev_b32_e32 v1, 4, v0
	v_and_b32_e32 v2, 0x3f0, v1
	v_mov_b32_e32 v3, 0
	v_lshl_add_u64 v[2:3], s[46:47], 0, v[2:3]
	v_lshl_add_u64 v[14:15], v[2:3], 0, s[0:1]
	s_mov_b64 s[0:1], 0x3000
	v_lshl_add_u64 v[16:17], v[2:3], 0, s[0:1]
	s_mov_b64 s[0:1], 0x3400
	v_lshl_add_u64 v[18:19], v[2:3], 0, s[0:1]
	s_mov_b64 s[0:1], 0x3800
	v_lshl_add_u64 v[20:21], v[2:3], 0, s[0:1]
	s_mov_b64 s[0:1], 0x3c00
	v_lshl_add_u64 v[22:23], v[2:3], 0, s[0:1]
	v_lshlrev_b64 v[2:3], 13, v[12:13]
	v_lshl_or_b32 v2, v4, 4, v2
	v_lshl_add_u64 v[0:1], s[28:29], 0, v[2:3]
	s_mov_b64 s[0:1], 0x1000
	v_lshl_add_u64 v[24:25], v[0:1], 0, s[0:1]
	v_lshlrev_b64 v[0:1], 12, v[12:13]
	v_lshl_or_b32 v0, v4, 3, v0
	v_lshl_add_u64 v[0:1], s[30:31], 0, v[0:1]
	s_mov_b64 s[0:1], 0x15550800
	v_lshl_add_u64 v[26:27], v[0:1], 0, s[0:1]
	v_mov_b32_e32 v13, 0x358637bd
	s_mov_b32 s0, 0xf800000
	s_movk_i32 s1, 0x7fff
	global_load_dwordx4 v[100:103], v[14:15], off
	global_load_dwordx4 v[104:107], v[14:15], off offset:1024
	global_load_dwordx4 v[108:111], v[14:15], off offset:2048
	global_load_dwordx4 v[112:115], v[14:15], off offset:3072
	global_load_dwordx4 v[116:119], v[16:17], off
	global_load_dwordx4 v[120:123], v[18:19], off
	global_load_dwordx4 v[124:127], v[20:21], off
	global_load_dwordx4 v[128:131], v[22:23], off
	global_load_dwordx4 v[196:199], v[24:25], off offset:-4096
	global_load_dwordx4 v[200:203], v[24:25], off offset:-3072
	global_load_dwordx4 v[204:207], v[24:25], off offset:-2048
	global_load_dwordx4 v[208:211], v[24:25], off offset:-1024
	global_load_dwordx4 v[212:215], v[24:25], off
	global_load_dwordx4 v[216:219], v[24:25], off offset:1024
	global_load_dwordx4 v[220:223], v[24:25], off offset:2048
	global_load_dwordx4 v[224:227], v[24:25], off offset:3072
	v_add_u32_e32 v12, s42, v12
	v_lshl_add_u64 v[24:25], v[24:25], 0, s[12:13]
	v_cmp_lt_i32_e32 vcc, s1, v12
	s_mov_b64 s[88:89], vcc
	s_mov_b64 s[86:87], exec
	s_andn2_b64 exec, exec, s[88:89]
	global_load_dwordx4 v[164:167], v[24:25], off offset:-4096
	global_load_dwordx4 v[168:171], v[24:25], off offset:-3072
	global_load_dwordx4 v[172:175], v[24:25], off offset:-2048
	global_load_dwordx4 v[176:179], v[24:25], off offset:-1024
	global_load_dwordx4 v[180:183], v[24:25], off
	global_load_dwordx4 v[184:187], v[24:25], off offset:1024
	global_load_dwordx4 v[188:191], v[24:25], off offset:2048
	global_load_dwordx4 v[228:231], v[24:25], off offset:3072
	s_mov_b64 exec, s[86:87]
	v_add_u32_e32 v12, s42, v12
	v_lshl_add_u64 v[24:25], v[24:25], 0, s[12:13]
	s_waitcnt vmcnt(0)

; __device__ __forceinline__ unsigned xb_ld(unsigned* p)              { return __hip_atomic_load(p, __ATOMIC_RELAXED, __HIP_MEMORY_SCOPE_AGENT); }
; __device__ __forceinline__ unsigned xb_add(unsigned* p, unsigned v) { return __hip_atomic_fetch_add(p, v, __ATOMIC_RELAXED, __HIP_MEMORY_SCOPE_AGENT); }
; __device__ __forceinline__ void xcd_barrier_complete(unsigned* bar, unsigned x, unsigned& nloc, unsigned& nx) {
;     const unsigned G = gridDim.x * gridDim.y * gridDim.z;
;     unsigned sum, cnt, mine, sp = 0u;
;     for (;;) {
;         sum = 0u; cnt = 0u; mine = 0u;
; #pragma unroll
;         for (unsigned j = 0; j < 16; ++j) { const unsigned c = xb_ld(&bar[XB_XCNT(j)]); sum += c; cnt += (c > 0u) ? 1u : 0u; mine = (j == x) ? c : mine; }
; __device__ __forceinline__ void xcd_barrier(const XcdBarrier& b) {
;     asm volatile("s_waitcnt vmcnt(0)" ::: "memory");
;     __syncthreads();
;     if (threadIdx.x == 0) {
;         unsigned* bar = b.bar;
;         __builtin_amdgcn_s_waitcnt(0);
;         unsigned nloc = b.st[0], nx = b.st[1];
;         if (nloc == 0u) { xcd_barrier_complete(bar, b.x, nloc, nx); b.st[0] = nloc; b.st[1] = nx; }
;         const unsigned old = xb_add(&bar[XB_XSUB(b.x)], 1u);
.Lmy_rms3x_4:
.LBB0_2426:
	s_or_b64 exec, exec, s[10:11]
	s_waitcnt vmcnt(0)
	s_barrier
	s_mov_b64 s[8:9], exec
	v_readlane_b32 s0, v248, 20
	v_readlane_b32 s1, v248, 21
	s_and_b64 s[0:1], s[8:9], s[0:1]
	s_mov_b64 exec, s[0:1]
	s_cbranch_execz .LBB0_2478
	s_add_i32 s0, 0, 0x22000
	v_mov_b32_e32 v0, s0
	s_waitcnt vmcnt(0) expcnt(0) lgkmcnt(0)
	ds_read_b32 v2, v0
	s_add_i32 s0, 0, 0x22004
	v_mov_b32_e32 v0, s0
	ds_read_b32 v0, v0
	s_waitcnt lgkmcnt(1)
	v_cmp_ne_u32_e32 vcc, 0, v2
	s_cbranch_vccnz .LBB0_2442
	v_readlane_b32 s0, v248, 0
	v_readlane_b32 s1, v248, 1
	s_load_dword s1, s[0:1], 0x14
	s_mov_b32 s0, 1
	v_mov_b32_e32 v16, 0
	s_waitcnt lgkmcnt(0)
	s_lshr_b32 s12, s1, 16
	s_and_b32 s1, s1, 0xffff
	s_cmp_lg_u32 s1, 0
	s_cselect_b64 s[10:11], -1, 0
	s_cmp_lg_u64 s[10:11], 0
	s_addc_u32 s1, s69, 0
	s_cmp_lg_u32 s12, 0
	s_cselect_b64 s[10:11], -1, 0
	s_cmp_lg_u64 s[10:11], 0
	s_mul_i32 s1, s1, s68
	s_addc_u32 s10, s94, 0
	s_mul_i32 s1, s1, s10
	s_add_u32 s10, s30, 0x3e150a00
	s_addc_u32 s11, s31, 0
	s_add_u32 s12, s30, 0x3e150c00
	s_addc_u32 s13, s31, 0
	s_add_u32 s14, s30, 0x3e150d00
	s_addc_u32 s15, s31, 0
	s_add_u32 s16, s30, 0x3e150e00
	s_addc_u32 s17, s31, 0
	s_add_u32 s18, s30, 0x3e150f00
	s_addc_u32 s19, s31, 0
	s_add_u32 s20, s30, 0x3e151000
	s_addc_u32 s21, s31, 0
	s_add_u32 s22, s30, 0x3e151100
	s_addc_u32 s23, s31, 0
	s_add_u32 s24, s30, 0x3e151200
	s_addc_u32 s25, s31, 0
	s_add_u32 s36, s30, 0x3e151300
	s_addc_u32 s37, s31, 0
	s_add_u32 s38, s30, 0x3e151400
	s_addc_u32 s39, s31, 0
	s_add_u32 s46, s30, 0x3e151500
	s_addc_u32 s47, s31, 0
	s_add_u32 s54, s30, 0x3e151600
	s_addc_u32 s55, s31, 0
	s_add_u32 s56, s30, 0x3e151700
	s_addc_u32 s57, s31, 0
	s_add_u32 s58, s30, 0x3e151800
	s_addc_u32 s59, s31, 0
	s_add_u32 s64, s30, 0x3e151900
	s_addc_u32 s65, s31, 0
	s_add_u32 s66, s30, 0x3e151a00
	s_addc_u32 s67, s31, 0
	s_add_u32 s78, s30, 0x3e151b00
	s_addc_u32 s79, s31, 0
	s_branch .LBB0_2430

; __device__ __forceinline__ int opaque_tid() { int t = threadIdx.x; asm volatile("" : "+v"(t)); return t; }
; template <bool F32OUT>
; __device__ __forceinline__ void rmsnorm_rows(const float* x, const float* w, bf16_t* outb, float* outf) {
;     const int tid_ = opaque_tid(); const int lane = tid_ & 63, gw = blockIdx.x * 8 + (tid_ >> 6), nw = gridDim.x * 8;
;     for (int row = gw; row < T_; row += nw) {
;         const float* xr = x + (size_t)row * D_; f32x4 v[8]; float ss = 0.f;
; #pragma unroll
;         for (int i = 0; i < 8; ++i) { v[i] = *(const f32x4*)(xr + i * 256 + lane * 4); ss += v[i][0] * v[i][0] + v[i][1] * v[i][1] + v[i][2] * v[i][2] + v[i][3] * v[i][3]; }
.LBB0_3022:
	s_or_b64 exec, exec, s[8:9]
	s_waitcnt lgkmcnt(0)
	v_mov_b32_e32 v0, v192
	s_barrier
	s_mov_b32 s0, 0x8000
	v_mov_b32_e32 v0, v192
	s_nop 0
	v_ashrrev_i32_e32 v1, 6, v0
	v_add_u32_e32 v12, s92, v1
	v_cmp_gt_i32_e32 vcc, s0, v12
	s_and_saveexec_b64 s[10:11], vcc
	s_cbranch_execz .LBB0_3025
	v_mbcnt_hi_u32_b32 v1, -1, v193
	v_and_b32_e32 v2, 64, v1
	v_add_u32_e32 v2, 64, v2
	v_xor_b32_e32 v3, 32, v1
	v_cmp_lt_i32_e32 vcc, v3, v2
	s_mov_b64 s[0:1], 0x6000
	v_ashrrev_i32_e32 v13, 31, v12
	v_cndmask_b32_e32 v3, v1, v3, vcc
	v_lshlrev_b32_e32 v28, 2, v3
	v_xor_b32_e32 v3, 16, v1
	v_cmp_lt_i32_e32 vcc, v3, v2
	v_and_b32_e32 v4, 63, v0
	s_ashr_i32 s43, s42, 31
	v_cndmask_b32_e32 v3, v1, v3, vcc
	v_lshlrev_b32_e32 v29, 2, v3
	v_xor_b32_e32 v3, 8, v1
	v_cmp_lt_i32_e32 vcc, v3, v2
	s_lshl_b64 s[12:13], s[42:43], 13
	s_lshl_b64 s[14:15], s[42:43], 12
	v_cndmask_b32_e32 v3, v1, v3, vcc
	v_lshlrev_b32_e32 v30, 2, v3
	v_xor_b32_e32 v3, 4, v1
	v_cmp_lt_i32_e32 vcc, v3, v2
	s_mov_b64 s[16:17], 0
	v_mov_b32_e32 v34, 0x260
	v_cndmask_b32_e32 v3, v1, v3, vcc
	v_lshlrev_b32_e32 v31, 2, v3
	v_xor_b32_e32 v3, 2, v1
	v_cmp_lt_i32_e32 vcc, v3, v2
	s_nop 1
	v_cndmask_b32_e32 v3, v1, v3, vcc
	v_lshlrev_b32_e32 v32, 2, v3
	v_xor_b32_e32 v3, 1, v1
	v_cmp_lt_i32_e32 vcc, v3, v2
	s_nop 1
	v_cndmask_b32_e32 v1, v1, v3, vcc
	v_lshlrev_b32_e32 v33, 2, v1
	v_lshlrev_b32_e32 v1, 4, v0
	v_and_b32_e32 v2, 0x3f0, v1
	v_mov_b32_e32 v3, 0
	v_lshl_add_u64 v[2:3], s[40:41], 0, v[2:3]
	v_lshl_add_u64 v[14:15], v[2:3], 0, s[0:1]
	s_mov_b64 s[0:1], 0x7000
	v_lshl_add_u64 v[16:17], v[2:3], 0, s[0:1]
	s_mov_b64 s[0:1], 0x7400
	v_lshl_add_u64 v[18:19], v[2:3], 0, s[0:1]
	s_mov_b64 s[0:1], 0x7800
	v_lshl_add_u64 v[20:21], v[2:3], 0, s[0:1]
	s_mov_b64 s[0:1], 0x7c00
	v_lshl_add_u64 v[22:23], v[2:3], 0, s[0:1]
	v_lshlrev_b64 v[2:3], 13, v[12:13]
	v_lshl_or_b32 v2, v4, 4, v2
	v_lshl_add_u64 v[0:1], s[28:29], 0, v[2:3]
	s_mov_b64 s[0:1], 0x1000
	v_lshl_add_u64 v[24:25], v[0:1], 0, s[0:1]
	v_lshlrev_b64 v[0:1], 12, v[12:13]
	v_lshl_or_b32 v0, v4, 3, v0
	v_lshl_add_u64 v[0:1], s[30:31], 0, v[0:1]
	s_mov_b64 s[0:1], 0x15550800
	v_lshl_add_u64 v[26:27], v[0:1], 0, s[0:1]
	v_mov_b32_e32 v13, 0x358637bd
	s_mov_b32 s0, 0xf800000
	s_movk_i32 s1, 0x7fff
	global_load_dwordx4 v[100:103], v[14:15], off
	global_load_dwordx4 v[104:107], v[14:15], off offset:1024
	global_load_dwordx4 v[108:111], v[14:15], off offset:2048
	global_load_dwordx4 v[112:115], v[14:15], off offset:3072
	global_load_dwordx4 v[116:119], v[16:17], off
	global_load_dwordx4 v[120:123], v[18:19], off
	global_load_dwordx4 v[124:127], v[20:21], off
	global_load_dwordx4 v[128:131], v[22:23], off
	global_load_dwordx4 v[196:199], v[24:25], off offset:-4096
	global_load_dwordx4 v[200:203], v[24:25], off offset:-3072
	global_load_dwordx4 v[204:207], v[24:25], off offset:-2048
	global_load_dwordx4 v[208:211], v[24:25], off offset:-1024
	global_load_dwordx4 v[212:215], v[24:25], off
	global_load_dwordx4 v[216:219], v[24:25], off offset:1024
	global_load_dwordx4 v[220:223], v[24:25], off offset:2048
	global_load_dwordx4 v[224:227], v[24:25], off offset:3072
	v_add_u32_e32 v12, s42, v12
	v_lshl_add_u64 v[24:25], v[24:25], 0, s[12:13]
	v_cmp_lt_i32_e32 vcc, s1, v12
	s_mov_b64 s[88:89], vcc
	s_mov_b64 s[86:87], exec
	s_andn2_b64 exec, exec, s[88:89]
	global_load_dwordx4 v[164:167], v[24:25], off offset:-4096
	global_load_dwordx4 v[168:171], v[24:25], off offset:-3072
	global_load_dwordx4 v[172:175], v[24:25], off offset:-2048
	global_load_dwordx4 v[176:179], v[24:25], off offset:-1024
	global_load_dwordx4 v[180:183], v[24:25], off
	global_load_dwordx4 v[184:187], v[24:25], off offset:1024
	global_load_dwordx4 v[188:191], v[24:25], off offset:2048
	global_load_dwordx4 v[228:231], v[24:25], off offset:3072
	s_mov_b64 exec, s[86:87]
	v_add_u32_e32 v12, s42, v12
	v_lshl_add_u64 v[24:25], v[24:25], 0, s[12:13]
	s_waitcnt vmcnt(0)

; __device__ __forceinline__ unsigned xb_ld(unsigned* p)              { return __hip_atomic_load(p, __ATOMIC_RELAXED, __HIP_MEMORY_SCOPE_AGENT); }
; __device__ __forceinline__ unsigned xb_add(unsigned* p, unsigned v) { return __hip_atomic_fetch_add(p, v, __ATOMIC_RELAXED, __HIP_MEMORY_SCOPE_AGENT); }
; __device__ __forceinline__ void xcd_barrier_complete(unsigned* bar, unsigned x, unsigned& nloc, unsigned& nx) {
;     const unsigned G = gridDim.x * gridDim.y * gridDim.z;
;     unsigned sum, cnt, mine, sp = 0u;
;     for (;;) {
;         sum = 0u; cnt = 0u; mine = 0u;
; #pragma unroll
;         for (unsigned j = 0; j < 16; ++j) { const unsigned c = xb_ld(&bar[XB_XCNT(j)]); sum += c; cnt += (c > 0u) ? 1u : 0u; mine = (j == x) ? c : mine; }
; __device__ __forceinline__ void xcd_barrier(const XcdBarrier& b) {
;     asm volatile("s_waitcnt vmcnt(0)" ::: "memory");
;     __syncthreads();
;     if (threadIdx.x == 0) {
;         unsigned* bar = b.bar;
;         __builtin_amdgcn_s_waitcnt(0);
;         unsigned nloc = b.st[0], nx = b.st[1];
;         if (nloc == 0u) { xcd_barrier_complete(bar, b.x, nloc, nx); b.st[0] = nloc; b.st[1] = nx; }
;         const unsigned old = xb_add(&bar[XB_XSUB(b.x)], 1u);
.Lmy_rms3x_5:
.LBB0_3025:
	s_or_b64 exec, exec, s[10:11]
	s_waitcnt vmcnt(0)
	s_barrier
	s_mov_b64 s[8:9], exec
	v_readlane_b32 s0, v248, 20
	v_readlane_b32 s1, v248, 21
	s_and_b64 s[0:1], s[8:9], s[0:1]
	s_mov_b64 exec, s[0:1]
	s_cbranch_execz .LBB0_3077
	s_add_i32 s0, 0, 0x22000
	v_mov_b32_e32 v0, s0
	s_waitcnt vmcnt(0) expcnt(0) lgkmcnt(0)
	ds_read_b32 v2, v0
	s_add_i32 s0, 0, 0x22004
	v_mov_b32_e32 v0, s0
	ds_read_b32 v0, v0
	s_waitcnt lgkmcnt(1)
	v_cmp_ne_u32_e32 vcc, 0, v2
	s_cbranch_vccnz .LBB0_3041
	v_readlane_b32 s0, v248, 0
	v_readlane_b32 s1, v248, 1
	s_load_dword s1, s[0:1], 0x14
	s_mov_b32 s0, 1
	v_mov_b32_e32 v16, 0
	s_waitcnt lgkmcnt(0)
	s_lshr_b32 s12, s1, 16
	s_and_b32 s1, s1, 0xffff
	s_cmp_lg_u32 s1, 0
	s_cselect_b64 s[10:11], -1, 0
	s_cmp_lg_u64 s[10:11], 0
	s_addc_u32 s1, s69, 0
	s_cmp_lg_u32 s12, 0
	s_cselect_b64 s[10:11], -1, 0
	s_cmp_lg_u64 s[10:11], 0
	s_mul_i32 s1, s1, s68
	s_addc_u32 s10, s94, 0
	s_mul_i32 s1, s1, s10
	s_add_u32 s10, s30, 0x3e150a00
	s_addc_u32 s11, s31, 0
	s_add_u32 s12, s30, 0x3e150c00
	s_addc_u32 s13, s31, 0
	s_add_u32 s14, s30, 0x3e150d00
	s_addc_u32 s15, s31, 0
	s_add_u32 s16, s30, 0x3e150e00
	s_addc_u32 s17, s31, 0
	s_add_u32 s18, s30, 0x3e150f00
	s_addc_u32 s19, s31, 0
	s_add_u32 s20, s30, 0x3e151000
	s_addc_u32 s21, s31, 0
	s_add_u32 s22, s30, 0x3e151100
	s_addc_u32 s23, s31, 0
	s_add_u32 s24, s30, 0x3e151200
	s_addc_u32 s25, s31, 0
	s_add_u32 s36, s30, 0x3e151300
	s_addc_u32 s37, s31, 0
	s_add_u32 s38, s30, 0x3e151400
	s_addc_u32 s39, s31, 0
	s_add_u32 s40, s30, 0x3e151500
	s_addc_u32 s41, s31, 0
	s_add_u32 s46, s30, 0x3e151600
	s_addc_u32 s47, s31, 0
	s_add_u32 s50, s30, 0x3e151700
	s_addc_u32 s51, s31, 0
	s_add_u32 s52, s30, 0x3e151800
	s_addc_u32 s53, s31, 0
	s_add_u32 s54, s30, 0x3e151900
	s_addc_u32 s55, s31, 0
	s_add_u32 s56, s30, 0x3e151a00
	s_addc_u32 s57, s31, 0
	s_add_u32 s58, s30, 0x3e151b00
	s_addc_u32 s59, s31, 0
	s_branch .LBB0_3029
